# attention: next item's K/V staging loads prefetched into free VGPRs during the current item's compute (counted vmcnt), on top of early L1 invalidate in seams
# baseline (speedup 1.0000x reference)
.LBB0_519:
	s_cmp_lt_i32 s78, 6
	s_cselect_b64 s[2:3], -1, 0
	s_add_u32 s34, s76, 0x100000
	s_addc_u32 s35, s77, 0
	s_add_u32 s30, s76, 0x6000000
	s_addc_u32 s31, s77, 0
	s_and_b64 s[36:37], s[2:3], s[0:1]
	s_andn2_b64 vcc, exec, s[36:37]
	s_cbranch_vccnz .LBB0_530
	s_cmpk_gt_i32 s54, 0x5ff
	s_cbranch_scc1 .LBB0_530
	v_lshrrev_b32_e32 v4, 4, v170
	v_mov_b32_e32 v1, 0
	v_and_b32_e32 v2, 48, v170
	v_mov_b32_e32 v3, v1
	v_lshlrev_b32_e32 v68, 2, v4
	v_and_b32_e32 v61, 15, v171
	v_lshlrev_b32_e32 v0, 3, v4
	v_lshl_add_u64 v[56:57], s[94:95], 0, v[2:3]
	v_or_b32_e32 v3, 0xffffffc0, v68
	v_sub_u32_e32 v3, v3, v61
	v_add_u32_e32 v4, 0, v0
	v_lshl_add_u64 v[58:59], s[94:95], 0, v[0:1]
	v_and_b32_e32 v0, 7, v171
	v_lshl_add_u32 v62, v0, 4, 0
	s_movk_i32 s0, 0x1930
	v_sub_u32_e32 v12, 0, v3
	s_movk_i32 s18, 0x41
	v_mad_u32_u24 v69, v0, s0, v62
	v_cmp_gt_u32_e64 s[0:1], s18, v12
	v_cvt_f32_u32_e32 v70, v12
	v_not_b32_e32 v12, v3
	v_cvt_f32_u32_e32 v71, v12
	v_sub_u32_e32 v12, -2, v3
	v_cvt_f32_u32_e32 v72, v12
	v_sub_u32_e32 v12, -3, v3
	v_cvt_f32_u32_e32 v73, v12
	v_sub_u32_e32 v12, -16, v3
	v_cvt_f32_u32_e32 v74, v12
	v_sub_u32_e32 v12, 0xffffffef, v3
	v_cvt_f32_u32_e32 v75, v12
	v_sub_u32_e32 v12, 0xffffffee, v3
	v_cvt_f32_u32_e32 v76, v12
	v_sub_u32_e32 v12, 0xffffffed, v3
	v_cvt_f32_u32_e32 v77, v12
	v_sub_u32_e32 v12, 0xffffffe0, v3
	v_cvt_f32_u32_e32 v78, v12
	v_sub_u32_e32 v12, 0xffffffdf, v3
	v_cvt_f32_u32_e32 v79, v12
	v_sub_u32_e32 v12, 0xffffffde, v3
	v_cvt_f32_u32_e32 v80, v12
	v_sub_u32_e32 v12, 0xffffffdd, v3
	v_cvt_f32_u32_e32 v81, v12
	v_sub_u32_e32 v12, 0xffffffd0, v3
	v_cvt_f32_u32_e32 v82, v12
	v_add_u32_e32 v12, 49, v3
	v_sub_u32_e32 v13, 0xffffffcf, v3
	v_max_i32_e32 v12, v12, v13
	v_cvt_f32_u32_e32 v83, v12
	v_add_u32_e32 v12, 50, v3
	v_sub_u32_e32 v13, 0xffffffce, v3
	v_max_i32_e32 v12, v12, v13
	v_cvt_f32_u32_e32 v84, v12
	v_add_u32_e32 v12, 51, v3
	v_sub_u32_e32 v13, 0xffffffcd, v3
	v_max_i32_e32 v12, v12, v13
	v_cvt_f32_u32_e32 v85, v12
	v_add_u32_e32 v12, 64, v3
	v_sub_u32_e32 v13, 0xffffffc0, v3
	v_max_i32_e32 v12, v12, v13
	v_cvt_f32_u32_e32 v86, v12
	v_add_u32_e32 v12, 0x41, v3
	v_sub_u32_e32 v13, 0xffffffbf, v3
	v_max_i32_e32 v12, v12, v13
	v_cvt_f32_u32_e32 v87, v12
	v_add_u32_e32 v12, 0x42, v3
	v_sub_u32_e32 v13, 0xffffffbe, v3
	v_max_i32_e32 v12, v12, v13
	v_cvt_f32_u32_e32 v88, v12
	v_add_u32_e32 v12, 0x43, v3
	v_sub_u32_e32 v13, 0xffffffbd, v3
	v_max_i32_e32 v12, v12, v13
	v_cvt_f32_u32_e32 v89, v12
	v_add_u32_e32 v12, 0x50, v3
	v_cvt_f32_u32_e32 v90, v12
	v_add_u32_e32 v12, 0x51, v3
	v_cvt_f32_u32_e32 v91, v12
	v_add_u32_e32 v12, 0x52, v3
	v_cvt_f32_u32_e32 v92, v12
	v_add_u32_e32 v12, 0x53, v3
	v_cvt_f32_u32_e32 v93, v12
	v_add_u32_e32 v12, 0x60, v3
	v_cvt_f32_u32_e32 v94, v12
	v_add_u32_e32 v12, 0x61, v3
	v_cvt_f32_u32_e32 v95, v12
	v_add_u32_e32 v12, 0x62, v3
	v_cvt_f32_u32_e32 v96, v12
	v_add_u32_e32 v12, 0x63, v3
	v_cvt_f32_u32_e32 v97, v12
	v_add_u32_e32 v12, 0x70, v3
	v_cvt_f32_u32_e32 v98, v12
	v_add_u32_e32 v12, 0x71, v3
	s_add_i32 s20, s55, 2
	s_add_i32 s21, s55, 4
	s_add_i32 s22, s55, 6
	s_add_i32 s23, s55, 8
	v_cvt_f32_u32_e32 v99, v12
	v_add_u32_e32 v12, 0x72, v3
	s_lshl_b32 s45, s20, 4
	s_lshl_b32 s47, s21, 4
	s_lshl_b32 s49, s22, 4
	s_lshl_b32 s51, s23, 4
	v_cmp_gt_u32_e64 s[8:9], s18, v12
	v_cvt_f32_u32_e32 v100, v12
	v_add_u32_e32 v12, 0x73, v3
	v_lshl_add_u32 v111, s20, 5, v4
	v_lshl_add_u32 v112, s21, 5, v4
	v_lshl_add_u32 v113, s22, 5, v4
	v_lshl_add_u32 v114, s23, 5, v4
	s_add_i32 s20, s55, 10
	s_add_i32 s21, s55, 12
	s_add_i32 s22, s55, 14
	s_add_i32 s23, s55, 16
	v_cmp_gt_u32_e64 s[10:11], s18, v12
	v_cvt_f32_u32_e32 v101, v12
	v_add_u32_e32 v12, 0x80, v3
	v_lshl_add_u32 v107, s55, 5, v4
	v_lshl_add_u32 v115, s20, 5, v4
	v_lshl_add_u32 v116, s21, 5, v4
	v_lshl_add_u32 v117, s22, 5, v4
	v_lshl_add_u32 v118, s23, 5, v4
	v_mbcnt_lo_u32_b32 v4, -1, 0
	s_movk_i32 s2, 0xffbe
	s_movk_i32 s4, 0xffbd
	s_movk_i32 s6, 0xffbc
	v_cmp_gt_u32_e64 s[12:13], s18, v12
	v_cvt_f32_u32_e32 v102, v12
	v_add_u32_e32 v12, 0x81, v3
	v_mbcnt_hi_u32_b32 v4, -1, v4
	v_cmp_lt_u32_e64 s[2:3], s2, v3
	v_cmp_lt_u32_e64 s[4:5], s4, v3
	v_cmp_lt_u32_e64 s[6:7], s6, v3
	v_cmp_gt_u32_e64 s[14:15], s18, v12
	v_cvt_f32_u32_e32 v103, v12
	v_add_u32_e32 v12, 0x82, v3
	v_add_u32_e32 v3, 0x83, v3
	v_and_b32_e32 v20, 64, v4
	v_cmp_gt_u32_e64 s[16:17], s18, v12
	v_cmp_gt_u32_e64 s[18:19], s18, v3
	v_cvt_f32_u32_e32 v105, v3
	s_movk_i32 s24, 0x328
	v_mov_b32_e32 v3, 0x3280
	v_xor_b32_e32 v19, 16, v4
	v_add_u32_e32 v20, 64, v20
	v_mad_u32_u24 v108, v61, s24, v3
	v_mov_b32_e32 v3, 0x6500
	s_lshl_b32 s53, s20, 4
	s_lshl_b32 s61, s21, 4
	v_cmp_lt_i32_e64 s[20:21], v19, v20
	s_lshl_b32 s42, s55, 4
	v_mad_u32_u24 v109, v61, s24, v3
	s_mov_b64 s[24:25], s[76:77]
	v_cndmask_b32_e64 v19, v4, v19, s[20:21]
	s_add_i32 s44, s42, 16
	s_add_i32 s46, s42, 48
	s_add_i32 s48, s42, 0x50
	s_add_i32 s50, s42, 0x70
	v_cvt_f32_u32_e32 v104, v12
	v_or_b32_e32 v3, 48, v170
	s_add_i32 s52, s42, 0x90
	s_add_i32 s60, s42, 0xb0
	s_add_i32 s74, s42, 0xd0
	s_lshl_b32 s75, s22, 4
	s_mov_b64 s[26:27], s[78:79]
	s_add_i32 s76, s42, 0xf0
	s_lshl_b32 s77, s23, 4
	v_lshlrev_b32_e32 v119, 2, v19
	v_xor_b32_e32 v19, 32, v4
	v_or_b32_e32 v63, s42, v61
	v_and_b32_e32 v2, 48, v171
	s_movk_i32 s43, 0x90
	v_or_b32_e32 v1, s44, v61
	v_or_b32_e32 v5, s45, v61
	v_or_b32_e32 v6, s46, v61
	v_or_b32_e32 v7, s47, v61
	v_or_b32_e32 v8, s48, v61
	v_or_b32_e32 v9, s49, v61
	v_or_b32_e32 v10, s50, v61
	v_or_b32_e32 v11, s51, v61
	v_mul_u32_u24_e32 v110, 0x328, v3
	v_or_b32_e32 v3, s52, v61
	v_or_b32_e32 v12, s53, v61
	v_or_b32_e32 v13, s60, v61
	v_or_b32_e32 v14, s61, v61
	v_or_b32_e32 v15, s74, v61
	v_or_b32_e32 v16, s75, v61
	v_or_b32_e32 v17, s76, v61
	v_or_b32_e32 v18, s77, v61
	v_cmp_lt_i32_e64 s[20:21], v19, v20
	v_add_u32_e32 v2, 0, v2
	v_lshlrev_b32_e32 v60, 3, v0
	v_mul_lo_u32 v0, v63, s43
	v_mul_lo_u32 v1, v1, s43
	v_mul_lo_u32 v5, v5, s43
	v_mul_lo_u32 v6, v6, s43
	v_mul_lo_u32 v7, v7, s43
	v_mul_lo_u32 v8, v8, s43
	v_mul_lo_u32 v9, v9, s43
	v_mul_lo_u32 v10, v10, s43
	v_mul_lo_u32 v11, v11, s43
	v_mul_lo_u32 v3, v3, s43
	v_mul_lo_u32 v12, v12, s43
	v_mul_lo_u32 v13, v13, s43
	v_mul_lo_u32 v14, v14, s43
	v_mul_lo_u32 v15, v15, s43
	v_mul_lo_u32 v16, v16, s43
	v_mul_lo_u32 v17, v17, s43
	v_mul_lo_u32 v18, v18, s43
	s_add_u32 s38, s24, 0x9000000
	s_mov_b64 s[66:67], s[26:27]
	v_cndmask_b32_e64 v4, v4, v19, s[20:21]
	v_cmp_gt_u32_e32 vcc, 16, v170
	v_mul_u32_u24_e32 v106, 0x328, v61
	s_mov_b64 s[64:65], s[24:25]
	s_addc_u32 s39, s25, 0
	v_lshlrev_b32_e32 v120, 2, v4
	v_add_u32_e32 v121, 0xfffffe00, v171
	v_lshrrev_b32_e32 v122, 2, v171
	s_movk_i32 s80, 0x600
	s_mov_b32 s81, 0xffff0000
	s_movk_i32 s82, 0xc00
	v_add_u32_e32 v123, v2, v0
	v_add_u32_e32 v124, v2, v1
	v_add_u32_e32 v125, v2, v5
	v_add_u32_e32 v126, v2, v6
	v_add_u32_e32 v127, v2, v7
	v_add_u32_e32 v128, v2, v8
	v_add_u32_e32 v129, v2, v9
	v_add_u32_e32 v130, v2, v10
	v_add_u32_e32 v131, v2, v11
	s_mov_b32 s83, 0xf149f2ca
	v_add_u32_e32 v132, v2, v3
	v_add_u32_e32 v133, v2, v12
	v_add_u32_e32 v134, v2, v13
	v_add_u32_e32 v135, v2, v14
	v_add_u32_e32 v136, v2, v15
	v_add_u32_e32 v137, v2, v16
	v_add_u32_e32 v138, v2, v17
	v_add_u32_e32 v139, v2, v18
	v_mov_b32_e32 v140, 0x42800000
	v_mov_b32_e32 v141, 0xf149f2ca
	s_mov_b32 s62, 0x3000000
	s_mov_b32 s63, 0
	s_lshr_b32 s87, s42, 3
	s_addk_i32 s87, 0x180
	s_mov_b32 s85, s54
	s_movk_i32 s32, 0x1000
	s_ashr_i32 s96, s85, 9
	s_lshl_b32 s96, s96, 1
	s_lshr_b32 s97, 16, s96
	s_add_i32 s97, s97, -1
	s_and_b32 s98, s85, 15
	s_sub_i32 s99, 4, s96
	s_lshr_b32 s99, s98, s99
	s_and_b32 s98, s97, s98
	s_lshl_b32 s98, s98, 8
	s_add_i32 s98, s98, 0xffffffc0
	s_lshl_b32 s97, s85, 5
	s_and_b32 s97, s97, 0x3000
	s_or_b32 s99, s99, s97
	s_lshr_b32 s97, s32, s96
	s_bfe_u32 s100, s85, 0x30004
	s_lshl_b32 s100, s100, 6
	s_and_b32 s101, s85, 0xfffffe00
	s_or_b32 s100, s100, s101
	v_or_b32_e32 v252, s100, v60
	v_mov_b32_e32 v253, 0
	v_and_b32_e32 v244, 0x1fe, v122
	v_add_u32_e32 v244, s98, v244
	v_cmp_lt_i32_e64 s[56:57], -1, v244
	v_cmp_gt_i32_e64 s[58:59], s97, v244
	v_or_b32_e32 v245, 1, v244
	s_and_b64 s[58:59], s[56:57], s[58:59]
	v_cmp_gt_i32_e64 s[70:71], s97, v245
	v_cndmask_b32_e64 v244, 0, v244, s[58:59]
	s_and_b64 s[56:57], s[56:57], s[70:71]
	v_lshlrev_b32_e32 v244, s96, v244
	v_add_u32_e32 v244, s99, v244
	v_cndmask_b32_e64 v245, 0, v245, s[56:57]
	v_mad_i64_i32 v[254:255], s[70:71], v244, s80, v[252:253]
	v_lshlrev_b32_e32 v245, s96, v245
	v_add_u32_e32 v245, s99, v245
	v_lshlrev_b64 v[254:255], 1, v[254:255]
	v_lshl_add_u64 v[254:255], s[30:31], 0, v[254:255]
	global_load_dwordx4 v[184:187], v[254:255], off nt
	v_lshl_add_u64 v[254:255], v[254:255], 0, s[62:63]
	global_load_dwordx4 v[192:195], v[254:255], off nt
	v_mad_i64_i32 v[254:255], s[70:71], v245, s80, v[252:253]
	v_lshlrev_b64 v[254:255], 1, v[254:255]
	v_lshl_add_u64 v[254:255], s[30:31], 0, v[254:255]
	global_load_dwordx4 v[188:191], v[254:255], off nt
	v_lshl_add_u64 v[254:255], v[254:255], 0, s[62:63]
	global_load_dwordx4 v[196:199], v[254:255], off nt
	v_add_u32_e32 v244, 128, v122
	v_and_b32_e32 v244, 0x1fe, v244
	v_add_u32_e32 v244, s98, v244
	v_cmp_lt_i32_e64 s[56:57], -1, v244
	v_cmp_gt_i32_e64 s[58:59], s97, v244
	v_or_b32_e32 v245, 1, v244
	s_and_b64 s[58:59], s[56:57], s[58:59]
	v_cmp_gt_i32_e64 s[70:71], s97, v245
	v_cndmask_b32_e64 v244, 0, v244, s[58:59]
	s_and_b64 s[56:57], s[56:57], s[70:71]
	v_lshlrev_b32_e32 v244, s96, v244
	v_add_u32_e32 v244, s99, v244
	v_cndmask_b32_e64 v245, 0, v245, s[56:57]
	v_mad_i64_i32 v[254:255], s[70:71], v244, s80, v[252:253]
	v_lshlrev_b32_e32 v245, s96, v245
	v_add_u32_e32 v245, s99, v245
	v_lshlrev_b64 v[254:255], 1, v[254:255]
	v_lshl_add_u64 v[254:255], s[30:31], 0, v[254:255]
	global_load_dwordx4 v[200:203], v[254:255], off nt
	v_lshl_add_u64 v[254:255], v[254:255], 0, s[62:63]
	global_load_dwordx4 v[208:211], v[254:255], off nt
	v_mad_i64_i32 v[254:255], s[70:71], v245, s80, v[252:253]
	v_lshlrev_b64 v[254:255], 1, v[254:255]
	v_lshl_add_u64 v[254:255], s[30:31], 0, v[254:255]
	global_load_dwordx4 v[204:207], v[254:255], off nt
	v_lshl_add_u64 v[254:255], v[254:255], 0, s[62:63]
	global_load_dwordx4 v[212:215], v[254:255], off nt
	v_add_u32_e32 v244, 256, v122
	v_and_b32_e32 v244, 0x1fe, v244
	v_add_u32_e32 v244, s98, v244
	v_cmp_lt_i32_e64 s[56:57], -1, v244
	v_cmp_gt_i32_e64 s[58:59], s97, v244
	v_or_b32_e32 v245, 1, v244
	s_and_b64 s[58:59], s[56:57], s[58:59]
	v_cmp_gt_i32_e64 s[70:71], s97, v245
	v_cndmask_b32_e64 v244, 0, v244, s[58:59]
	s_and_b64 s[56:57], s[56:57], s[70:71]
	v_lshlrev_b32_e32 v244, s96, v244
	v_add_u32_e32 v244, s99, v244
	v_cndmask_b32_e64 v245, 0, v245, s[56:57]
	v_mad_i64_i32 v[254:255], s[70:71], v244, s80, v[252:253]
	v_lshlrev_b32_e32 v245, s96, v245
	v_add_u32_e32 v245, s99, v245
	v_lshlrev_b64 v[254:255], 1, v[254:255]
	v_lshl_add_u64 v[254:255], s[30:31], 0, v[254:255]
	global_load_dwordx4 v[216:219], v[254:255], off nt
	v_lshl_add_u64 v[254:255], v[254:255], 0, s[62:63]
	global_load_dwordx4 v[224:227], v[254:255], off nt
	v_mad_i64_i32 v[254:255], s[70:71], v245, s80, v[252:253]
	v_lshlrev_b64 v[254:255], 1, v[254:255]
	v_lshl_add_u64 v[254:255], s[30:31], 0, v[254:255]
	global_load_dwordx4 v[220:223], v[254:255], off nt
	v_lshl_add_u64 v[254:255], v[254:255], 0, s[62:63]
	global_load_dwordx4 v[228:231], v[254:255], off nt
	s_mov_b64 exec, 0xff
	s_add_i32 s32, s98, s87
	v_mov_b32_e32 v244, s32
	v_cmp_lt_i32_e64 s[56:57], -1, v244
	v_cmp_gt_i32_e64 s[58:59], s97, v244
	v_or_b32_e32 v245, 1, v244
	s_and_b64 s[58:59], s[56:57], s[58:59]
	v_cmp_gt_i32_e64 s[70:71], s97, v245
	v_cndmask_b32_e64 v244, 0, v244, s[58:59]
	s_and_b64 s[56:57], s[56:57], s[70:71]
	v_lshlrev_b32_e32 v244, s96, v244
	v_add_u32_e32 v244, s99, v244
	v_cndmask_b32_e64 v245, 0, v245, s[56:57]
	v_mad_i64_i32 v[254:255], s[70:71], v244, s80, v[252:253]
	v_lshlrev_b32_e32 v245, s96, v245
	v_add_u32_e32 v245, s99, v245
	v_lshlrev_b64 v[254:255], 1, v[254:255]
	v_lshl_add_u64 v[254:255], s[30:31], 0, v[254:255]
	global_load_dwordx4 v[232:235], v[254:255], off nt
	v_lshl_add_u64 v[254:255], v[254:255], 0, s[62:63]
	global_load_dwordx4 v[240:243], v[254:255], off nt
	v_mad_i64_i32 v[254:255], s[70:71], v245, s80, v[252:253]
	v_lshlrev_b64 v[254:255], 1, v[254:255]
	v_lshl_add_u64 v[254:255], s[30:31], 0, v[254:255]
	global_load_dwordx4 v[236:239], v[254:255], off nt
	v_lshl_add_u64 v[254:255], v[254:255], 0, s[62:63]
	global_load_dwordx4 v[248:251], v[254:255], off nt
	s_mov_b64 exec, -1
	s_waitcnt vmcnt(0)
	s_branch .LBB0_523

.LBB0_523:
	s_ashr_i32 s26, s54, 9
	s_lshl_b32 s90, s26, 1
	s_lshr_b32 s21, 16, s90
	s_and_b32 s20, s54, 15
	s_sub_i32 s22, 4, s90
	s_add_i32 s21, s21, -1
	s_bfe_u32 s33, s54, 0x30004
	s_lshr_b32 s22, s20, s22
	s_and_b32 s20, s21, s20
	s_lshl_b32 s27, s20, 8
	s_and_b32 s20, s54, 0xfffffe00
	s_lshl_b32 s21, s33, 6
	s_or_b32 s28, s21, s20
	s_lshl_b32 s20, s54, 5
	s_and_b32 s20, s20, 0x3000
	s_ashr_i32 s29, s28, 31
	s_lshr_b32 s88, 0x1000, s90
	s_sub_i32 s89, s27, 64
	s_or_b32 s91, s22, s20
	s_barrier
	s_waitcnt vmcnt(22)
	v_and_b32_e32 v20, 0x1fe, v122
	v_add_u32_e32 v4, s89, v20
	v_cmp_lt_i32_e64 s[20:21], -1, v4
	v_cmp_gt_i32_e64 s[22:23], s88, v4
	v_or_b32_e32 v6, 1, v4
	s_and_b64 s[22:23], s[20:21], s[22:23]
	v_cmp_gt_i32_e64 s[24:25], s88, v6
	v_mad_u32_u24 v21, v20, s43, v62
	v_or_b32_e32 v5, 1, v20
	s_and_b64 s[20:21], s[20:21], s[24:25]
	v_cndmask_b32_e64 v184, 0, v184, s[22:23]
	v_cndmask_b32_e64 v185, 0, v185, s[22:23]
	v_cndmask_b32_e64 v186, 0, v186, s[22:23]
	v_cndmask_b32_e64 v187, 0, v187, s[22:23]
	ds_write_b128 v21, v[184:187]
	v_mad_u32_u24 v5, v5, s43, v62
	v_cndmask_b32_e64 v188, 0, v188, s[20:21]
	v_cndmask_b32_e64 v189, 0, v189, s[20:21]
	v_cndmask_b32_e64 v190, 0, v190, s[20:21]
	v_cndmask_b32_e64 v191, 0, v191, s[20:21]
	ds_write_b128 v5, v[188:191]
	v_cndmask_b32_e64 v192, 0, v192, s[22:23]
	v_cndmask_b32_e64 v193, 0, v193, s[22:23]
	v_cndmask_b32_e64 v194, 0, v194, s[22:23]
	v_cndmask_b32_e64 v195, 0, v195, s[22:23]
	v_cndmask_b32_e64 v196, 0, v196, s[20:21]
	v_cndmask_b32_e64 v197, 0, v197, s[20:21]
	v_cndmask_b32_e64 v198, 0, v198, s[20:21]
	v_cndmask_b32_e64 v199, 0, v199, s[20:21]
	v_lshl_add_u32 v7, v20, 1, v69
	v_and_b32_e32 v8, 0xffff, v192
	v_lshrrev_b32_e32 v9, 16, v192
	v_lshl_or_b32 v8, v196, 16, v8
	v_and_or_b32 v9, v196, s81, v9
	v_add_u32_e32 v10, 0xe100, v7
	ds_write2_b32 v10, v8, v9 offset1:202
	v_and_b32_e32 v8, 0xffff, v193
	v_lshrrev_b32_e32 v9, 16, v193
	v_lshl_or_b32 v8, v197, 16, v8
	v_and_or_b32 v9, v197, s81, v9
	v_add_u32_e32 v10, 0xe700, v7
	ds_write2_b32 v10, v8, v9 offset0:20 offset1:222
	v_and_b32_e32 v8, 0xffff, v194
	v_lshrrev_b32_e32 v9, 16, v194
	v_lshl_or_b32 v8, v198, 16, v8
	v_and_or_b32 v9, v198, s81, v9
	v_add_u32_e32 v10, 0xed00, v7
	ds_write2_b32 v10, v8, v9 offset0:40 offset1:242
	v_and_b32_e32 v8, 0xffff, v195
	v_lshrrev_b32_e32 v9, 16, v195
	v_lshl_or_b32 v8, v199, 16, v8
	v_and_or_b32 v9, v199, s81, v9
	v_add_u32_e32 v10, 0xf380, v7
	ds_write2_b32 v10, v8, v9 offset0:28 offset1:230
	s_waitcnt vmcnt(18)
	v_add_u32_e32 v20, 128, v122
	v_and_b32_e32 v20, 0x1fe, v20
	v_add_u32_e32 v4, s89, v20
	v_cmp_lt_i32_e64 s[20:21], -1, v4
	v_cmp_gt_i32_e64 s[22:23], s88, v4
	v_or_b32_e32 v6, 1, v4
	s_and_b64 s[22:23], s[20:21], s[22:23]
	v_cmp_gt_i32_e64 s[24:25], s88, v6
	v_mad_u32_u24 v21, v20, s43, v62
	v_or_b32_e32 v5, 1, v20
	s_and_b64 s[20:21], s[20:21], s[24:25]
	v_cndmask_b32_e64 v200, 0, v200, s[22:23]
	v_cndmask_b32_e64 v201, 0, v201, s[22:23]
	v_cndmask_b32_e64 v202, 0, v202, s[22:23]
	v_cndmask_b32_e64 v203, 0, v203, s[22:23]
	ds_write_b128 v21, v[200:203]
	v_mad_u32_u24 v5, v5, s43, v62
	v_cndmask_b32_e64 v204, 0, v204, s[20:21]
	v_cndmask_b32_e64 v205, 0, v205, s[20:21]
	v_cndmask_b32_e64 v206, 0, v206, s[20:21]
	v_cndmask_b32_e64 v207, 0, v207, s[20:21]
	ds_write_b128 v5, v[204:207]
	v_cndmask_b32_e64 v208, 0, v208, s[22:23]
	v_cndmask_b32_e64 v209, 0, v209, s[22:23]
	v_cndmask_b32_e64 v210, 0, v210, s[22:23]
	v_cndmask_b32_e64 v211, 0, v211, s[22:23]
	v_cndmask_b32_e64 v212, 0, v212, s[20:21]
	v_cndmask_b32_e64 v213, 0, v213, s[20:21]
	v_cndmask_b32_e64 v214, 0, v214, s[20:21]
	v_cndmask_b32_e64 v215, 0, v215, s[20:21]
	v_lshl_add_u32 v7, v20, 1, v69
	v_and_b32_e32 v8, 0xffff, v208
	v_lshrrev_b32_e32 v9, 16, v208
	v_lshl_or_b32 v8, v212, 16, v8
	v_and_or_b32 v9, v212, s81, v9
	v_add_u32_e32 v10, 0xe100, v7
	ds_write2_b32 v10, v8, v9 offset1:202
	v_and_b32_e32 v8, 0xffff, v209
	v_lshrrev_b32_e32 v9, 16, v209
	v_lshl_or_b32 v8, v213, 16, v8
	v_and_or_b32 v9, v213, s81, v9
	v_add_u32_e32 v10, 0xe700, v7
	ds_write2_b32 v10, v8, v9 offset0:20 offset1:222
	v_and_b32_e32 v8, 0xffff, v210
	v_lshrrev_b32_e32 v9, 16, v210
	v_lshl_or_b32 v8, v214, 16, v8
	v_and_or_b32 v9, v214, s81, v9
	v_add_u32_e32 v10, 0xed00, v7
	ds_write2_b32 v10, v8, v9 offset0:40 offset1:242
	v_and_b32_e32 v8, 0xffff, v211
	v_lshrrev_b32_e32 v9, 16, v211
	v_lshl_or_b32 v8, v215, 16, v8
	v_and_or_b32 v9, v215, s81, v9
	v_add_u32_e32 v10, 0xf380, v7
	ds_write2_b32 v10, v8, v9 offset0:28 offset1:230
	s_waitcnt vmcnt(14)
	v_add_u32_e32 v20, 256, v122
	v_and_b32_e32 v20, 0x1fe, v20
	v_add_u32_e32 v4, s89, v20
	v_cmp_lt_i32_e64 s[20:21], -1, v4
	v_cmp_gt_i32_e64 s[22:23], s88, v4
	v_or_b32_e32 v6, 1, v4
	s_and_b64 s[22:23], s[20:21], s[22:23]
	v_cmp_gt_i32_e64 s[24:25], s88, v6
	v_mad_u32_u24 v21, v20, s43, v62
	v_or_b32_e32 v5, 1, v20
	s_and_b64 s[20:21], s[20:21], s[24:25]
	v_cndmask_b32_e64 v216, 0, v216, s[22:23]
	v_cndmask_b32_e64 v217, 0, v217, s[22:23]
	v_cndmask_b32_e64 v218, 0, v218, s[22:23]
	v_cndmask_b32_e64 v219, 0, v219, s[22:23]
	ds_write_b128 v21, v[216:219]
	v_mad_u32_u24 v5, v5, s43, v62
	v_cndmask_b32_e64 v220, 0, v220, s[20:21]
	v_cndmask_b32_e64 v221, 0, v221, s[20:21]
	v_cndmask_b32_e64 v222, 0, v222, s[20:21]
	v_cndmask_b32_e64 v223, 0, v223, s[20:21]
	ds_write_b128 v5, v[220:223]
	v_cndmask_b32_e64 v224, 0, v224, s[22:23]
	v_cndmask_b32_e64 v225, 0, v225, s[22:23]
	v_cndmask_b32_e64 v226, 0, v226, s[22:23]
	v_cndmask_b32_e64 v227, 0, v227, s[22:23]
	v_cndmask_b32_e64 v228, 0, v228, s[20:21]
	v_cndmask_b32_e64 v229, 0, v229, s[20:21]
	v_cndmask_b32_e64 v230, 0, v230, s[20:21]
	v_cndmask_b32_e64 v231, 0, v231, s[20:21]
	v_lshl_add_u32 v7, v20, 1, v69
	v_and_b32_e32 v8, 0xffff, v224
	v_lshrrev_b32_e32 v9, 16, v224
	v_lshl_or_b32 v8, v228, 16, v8
	v_and_or_b32 v9, v228, s81, v9
	v_add_u32_e32 v10, 0xe100, v7
	ds_write2_b32 v10, v8, v9 offset1:202
	v_and_b32_e32 v8, 0xffff, v225
	v_lshrrev_b32_e32 v9, 16, v225
	v_lshl_or_b32 v8, v229, 16, v8
	v_and_or_b32 v9, v229, s81, v9
	v_add_u32_e32 v10, 0xe700, v7
	ds_write2_b32 v10, v8, v9 offset0:20 offset1:222
	v_and_b32_e32 v8, 0xffff, v226
	v_lshrrev_b32_e32 v9, 16, v226
	v_lshl_or_b32 v8, v230, 16, v8
	v_and_or_b32 v9, v230, s81, v9
	v_add_u32_e32 v10, 0xed00, v7
	ds_write2_b32 v10, v8, v9 offset0:40 offset1:242
	v_and_b32_e32 v8, 0xffff, v227
	v_lshrrev_b32_e32 v9, 16, v227
	v_lshl_or_b32 v8, v231, 16, v8
	v_and_or_b32 v9, v231, s81, v9
	v_add_u32_e32 v10, 0xf380, v7
	ds_write2_b32 v10, v8, v9 offset0:28 offset1:230
	s_waitcnt vmcnt(10)
	s_mov_b64 exec, 0xff
	v_mov_b32_e32 v20, s87
	v_add_u32_e32 v4, s89, v20
	v_cmp_lt_i32_e64 s[20:21], -1, v4
	v_cmp_gt_i32_e64 s[22:23], s88, v4
	v_or_b32_e32 v6, 1, v4
	s_and_b64 s[22:23], s[20:21], s[22:23]
	v_cmp_gt_i32_e64 s[24:25], s88, v6
	v_mad_u32_u24 v21, v20, s43, v62
	v_or_b32_e32 v5, 1, v20
	s_and_b64 s[20:21], s[20:21], s[24:25]
	v_cndmask_b32_e64 v232, 0, v232, s[22:23]
	v_cndmask_b32_e64 v233, 0, v233, s[22:23]
	v_cndmask_b32_e64 v234, 0, v234, s[22:23]
	v_cndmask_b32_e64 v235, 0, v235, s[22:23]
	ds_write_b128 v21, v[232:235]
	v_mad_u32_u24 v5, v5, s43, v62
	v_cndmask_b32_e64 v236, 0, v236, s[20:21]
	v_cndmask_b32_e64 v237, 0, v237, s[20:21]
	v_cndmask_b32_e64 v238, 0, v238, s[20:21]
	v_cndmask_b32_e64 v239, 0, v239, s[20:21]
	ds_write_b128 v5, v[236:239]
	v_cndmask_b32_e64 v240, 0, v240, s[22:23]
	v_cndmask_b32_e64 v241, 0, v241, s[22:23]
	v_cndmask_b32_e64 v242, 0, v242, s[22:23]
	v_cndmask_b32_e64 v243, 0, v243, s[22:23]
	v_cndmask_b32_e64 v248, 0, v248, s[20:21]
	v_cndmask_b32_e64 v249, 0, v249, s[20:21]
	v_cndmask_b32_e64 v250, 0, v250, s[20:21]
	v_cndmask_b32_e64 v251, 0, v251, s[20:21]
	v_lshl_add_u32 v7, v20, 1, v69
	v_and_b32_e32 v8, 0xffff, v240
	v_lshrrev_b32_e32 v9, 16, v240
	v_lshl_or_b32 v8, v248, 16, v8
	v_and_or_b32 v9, v248, s81, v9
	v_add_u32_e32 v10, 0xe100, v7
	ds_write2_b32 v10, v8, v9 offset1:202
	v_and_b32_e32 v8, 0xffff, v241
	v_lshrrev_b32_e32 v9, 16, v241
	v_lshl_or_b32 v8, v249, 16, v8
	v_and_or_b32 v9, v249, s81, v9
	v_add_u32_e32 v10, 0xe700, v7
	ds_write2_b32 v10, v8, v9 offset0:20 offset1:222
	v_and_b32_e32 v8, 0xffff, v242
	v_lshrrev_b32_e32 v9, 16, v242
	v_lshl_or_b32 v8, v250, 16, v8
	v_and_or_b32 v9, v250, s81, v9
	v_add_u32_e32 v10, 0xed00, v7
	ds_write2_b32 v10, v8, v9 offset0:40 offset1:242
	v_and_b32_e32 v8, 0xffff, v243
	v_lshrrev_b32_e32 v9, 16, v243
	v_lshl_or_b32 v8, v251, 16, v8
	v_and_or_b32 v9, v251, s81, v9
	v_add_u32_e32 v10, 0xf380, v7
	ds_write2_b32 v10, v8, v9 offset0:28 offset1:230
	s_mov_b64 exec, -1
	v_add_u32_e32 v4, s27, v63
	s_lshl_b64 s[22:23], s[28:29], 1
	v_lshlrev_b32_e32 v2, s90, v4
	v_lshl_add_u64 v[0:1], v[56:57], 0, s[22:23]
	v_add_u32_e32 v2, s91, v2
	v_mad_i64_i32 v[2:3], s[20:21], v2, s82, v[0:1]
	global_load_dwordx4 v[12:15], v[2:3], off nt
	global_load_dwordx4 v[20:23], v[2:3], off offset:64 nt
	v_add_u32_e32 v2, 0x80, v4
	v_lshlrev_b32_e32 v2, s90, v2
	v_add_u32_e32 v2, s91, v2
	v_mad_i64_i32 v[0:1], s[20:21], v2, s82, v[0:1]
	s_lshl_b32 s20, s26, 3
	s_or_b32 s20, s33, s20
	s_add_i32 s20, s20, 1
	v_cvt_f32_i32_e32 v8, s20
	s_mov_b32 s20, 0xc2fc0000
	s_lshl_b32 s24, 1, s90
	v_or_b32_e32 v54, s27, v61
	v_mul_f32_e32 v9, 0xbeaaaaab, v8
	v_cmp_gt_f32_e64 s[20:21], s20, v9
	global_load_dwordx4 v[4:7], v[0:1], off nt
	s_nop 0
	global_load_dwordx4 v[0:3], v[0:1], off offset:64 nt
	v_cndmask_b32_e64 v9, 0, v140, s[20:21]
	v_fmac_f32_e32 v9, 0xbeaaaaab, v8
	v_exp_f32_e32 v8, v9
	v_cvt_f32_u32_e32 v9, s24
	s_and_b64 s[20:21], s[20:21], exec
	s_cselect_b32 s20, 0xffffffc0, 0
	v_ldexp_f32 v8, v8, s20
	v_mul_f32_e32 v55, v8, v9
	v_add_u32_e32 v8, s42, v54
	v_lshlrev_b32_e32 v8, s90, v8
	s_waitcnt lgkmcnt(0)
	s_barrier
	v_readlane_b32 s32, v246, 48
	s_nop 0
	s_add_i32 s85, s54, s32
	s_cmpk_lt_i32 s85, 0x600
	s_cselect_b32 s85, s85, s54
	s_cselect_b32 s32, 0x1000, 0
	s_ashr_i32 s96, s85, 9
	s_lshl_b32 s96, s96, 1
	s_lshr_b32 s97, 16, s96
	s_add_i32 s97, s97, -1
	s_and_b32 s98, s85, 15
	s_sub_i32 s99, 4, s96
	s_lshr_b32 s99, s98, s99
	s_and_b32 s98, s97, s98
	s_lshl_b32 s98, s98, 8
	s_add_i32 s98, s98, 0xffffffc0
	s_lshl_b32 s97, s85, 5
	s_and_b32 s97, s97, 0x3000
	s_or_b32 s99, s99, s97
	s_lshr_b32 s97, s32, s96
	s_bfe_u32 s100, s85, 0x30004
	s_lshl_b32 s100, s100, 6
	s_and_b32 s101, s85, 0xfffffe00
	s_or_b32 s100, s100, s101
	v_or_b32_e32 v252, s100, v60
	v_mov_b32_e32 v253, 0
	v_and_b32_e32 v244, 0x1fe, v122
	v_add_u32_e32 v244, s98, v244
	v_cmp_lt_i32_e64 s[56:57], -1, v244
	v_cmp_gt_i32_e64 s[58:59], s97, v244
	v_or_b32_e32 v245, 1, v244
	s_and_b64 s[58:59], s[56:57], s[58:59]
	v_cmp_gt_i32_e64 s[70:71], s97, v245
	v_cndmask_b32_e64 v244, 0, v244, s[58:59]
	s_and_b64 s[56:57], s[56:57], s[70:71]
	v_lshlrev_b32_e32 v244, s96, v244
	v_add_u32_e32 v244, s99, v244
	v_cndmask_b32_e64 v245, 0, v245, s[56:57]
	v_mad_i64_i32 v[254:255], s[70:71], v244, s80, v[252:253]
	v_lshlrev_b32_e32 v245, s96, v245
	v_add_u32_e32 v245, s99, v245
	v_lshlrev_b64 v[254:255], 1, v[254:255]
	v_lshl_add_u64 v[254:255], s[30:31], 0, v[254:255]
	global_load_dwordx4 v[184:187], v[254:255], off nt
	v_lshl_add_u64 v[254:255], v[254:255], 0, s[62:63]
	global_load_dwordx4 v[192:195], v[254:255], off nt
	v_mad_i64_i32 v[254:255], s[70:71], v245, s80, v[252:253]
	v_lshlrev_b64 v[254:255], 1, v[254:255]
	v_lshl_add_u64 v[254:255], s[30:31], 0, v[254:255]
	global_load_dwordx4 v[188:191], v[254:255], off nt
	v_lshl_add_u64 v[254:255], v[254:255], 0, s[62:63]
	global_load_dwordx4 v[196:199], v[254:255], off nt
	v_add_u32_e32 v244, 128, v122
	v_and_b32_e32 v244, 0x1fe, v244
	v_add_u32_e32 v244, s98, v244
	v_cmp_lt_i32_e64 s[56:57], -1, v244
	v_cmp_gt_i32_e64 s[58:59], s97, v244
	v_or_b32_e32 v245, 1, v244
	s_and_b64 s[58:59], s[56:57], s[58:59]
	v_cmp_gt_i32_e64 s[70:71], s97, v245
	v_cndmask_b32_e64 v244, 0, v244, s[58:59]
	s_and_b64 s[56:57], s[56:57], s[70:71]
	v_lshlrev_b32_e32 v244, s96, v244
	v_add_u32_e32 v244, s99, v244
	v_cndmask_b32_e64 v245, 0, v245, s[56:57]
	v_mad_i64_i32 v[254:255], s[70:71], v244, s80, v[252:253]
	v_lshlrev_b32_e32 v245, s96, v245
	v_add_u32_e32 v245, s99, v245
	v_lshlrev_b64 v[254:255], 1, v[254:255]
	v_lshl_add_u64 v[254:255], s[30:31], 0, v[254:255]
	global_load_dwordx4 v[200:203], v[254:255], off nt
	v_lshl_add_u64 v[254:255], v[254:255], 0, s[62:63]
	global_load_dwordx4 v[208:211], v[254:255], off nt
	v_mad_i64_i32 v[254:255], s[70:71], v245, s80, v[252:253]
	v_lshlrev_b64 v[254:255], 1, v[254:255]
	v_lshl_add_u64 v[254:255], s[30:31], 0, v[254:255]
	global_load_dwordx4 v[204:207], v[254:255], off nt
	v_lshl_add_u64 v[254:255], v[254:255], 0, s[62:63]
	global_load_dwordx4 v[212:215], v[254:255], off nt
	v_add_u32_e32 v244, 256, v122
	v_and_b32_e32 v244, 0x1fe, v244
	v_add_u32_e32 v244, s98, v244
	v_cmp_lt_i32_e64 s[56:57], -1, v244
	v_cmp_gt_i32_e64 s[58:59], s97, v244
	v_or_b32_e32 v245, 1, v244
	s_and_b64 s[58:59], s[56:57], s[58:59]
	v_cmp_gt_i32_e64 s[70:71], s97, v245
	v_cndmask_b32_e64 v244, 0, v244, s[58:59]
	s_and_b64 s[56:57], s[56:57], s[70:71]
	v_lshlrev_b32_e32 v244, s96, v244
	v_add_u32_e32 v244, s99, v244
	v_cndmask_b32_e64 v245, 0, v245, s[56:57]
	v_mad_i64_i32 v[254:255], s[70:71], v244, s80, v[252:253]
	v_lshlrev_b32_e32 v245, s96, v245
	v_add_u32_e32 v245, s99, v245
	v_lshlrev_b64 v[254:255], 1, v[254:255]
	v_lshl_add_u64 v[254:255], s[30:31], 0, v[254:255]
	global_load_dwordx4 v[216:219], v[254:255], off nt
	v_lshl_add_u64 v[254:255], v[254:255], 0, s[62:63]
	global_load_dwordx4 v[224:227], v[254:255], off nt
	v_mad_i64_i32 v[254:255], s[70:71], v245, s80, v[252:253]
	v_lshlrev_b64 v[254:255], 1, v[254:255]
	v_lshl_add_u64 v[254:255], s[30:31], 0, v[254:255]
	global_load_dwordx4 v[220:223], v[254:255], off nt
	v_lshl_add_u64 v[254:255], v[254:255], 0, s[62:63]
	global_load_dwordx4 v[228:231], v[254:255], off nt
	s_mov_b64 exec, 0xff
	s_add_i32 s32, s98, s87
	v_mov_b32_e32 v244, s32
	v_cmp_lt_i32_e64 s[56:57], -1, v244
	v_cmp_gt_i32_e64 s[58:59], s97, v244
	v_or_b32_e32 v245, 1, v244
	s_and_b64 s[58:59], s[56:57], s[58:59]
	v_cmp_gt_i32_e64 s[70:71], s97, v245
	v_cndmask_b32_e64 v244, 0, v244, s[58:59]
	s_and_b64 s[56:57], s[56:57], s[70:71]
	v_lshlrev_b32_e32 v244, s96, v244
	v_add_u32_e32 v244, s99, v244
	v_cndmask_b32_e64 v245, 0, v245, s[56:57]
	v_mad_i64_i32 v[254:255], s[70:71], v244, s80, v[252:253]
	v_lshlrev_b32_e32 v245, s96, v245
	v_add_u32_e32 v245, s99, v245
	v_lshlrev_b64 v[254:255], 1, v[254:255]
	v_lshl_add_u64 v[254:255], s[30:31], 0, v[254:255]
	global_load_dwordx4 v[232:235], v[254:255], off nt
	v_lshl_add_u64 v[254:255], v[254:255], 0, s[62:63]
	global_load_dwordx4 v[240:243], v[254:255], off nt
	v_mad_i64_i32 v[254:255], s[70:71], v245, s80, v[252:253]
	v_lshlrev_b64 v[254:255], 1, v[254:255]
	v_lshl_add_u64 v[254:255], s[30:31], 0, v[254:255]
	global_load_dwordx4 v[236:239], v[254:255], off nt
	v_lshl_add_u64 v[254:255], v[254:255], 0, s[62:63]
	global_load_dwordx4 v[248:251], v[254:255], off nt
	s_mov_b64 exec, -1
	v_add_u32_e32 v52, s91, v8
	ds_read_b128 v[8:11], v123
	ds_read_b128 v[16:19], v123 offset:64
	s_ashr_i32 s27, s26, 31
	s_lshl_b64 s[20:21], s[26:27], 19
	s_add_u32 s20, s34, s20
	v_lshl_add_u64 v[64:65], v[58:59], 0, s[22:23]
	s_addc_u32 s21, s35, s21
	s_lshl_b32 s22, s33, 2
	s_add_u32 s40, s20, s22
	s_addc_u32 s41, s21, 0
	s_add_i32 s20, s89, s42
	s_cmp_gt_i32 s20, -1
	s_cselect_b64 s[22:23], -1, 0
	v_or_b32_e32 v53, s20, v68
	s_and_b64 s[24:25], s[0:1], s[22:23]
	v_cmp_gt_i32_e64 s[20:21], s88, v53
	s_and_b64 s[20:21], s[24:25], s[20:21]
	v_or_b32_e32 v67, 1, v53
	s_and_b64 s[24:25], s[2:3], s[22:23]
	s_waitcnt vmcnt(19) lgkmcnt(1)
	v_mfma_f32_16x16x32_bf16 v[8:11], v[8:11], v[12:15], 0
	s_waitcnt vmcnt(18) lgkmcnt(0)
	v_mfma_f32_16x16x32_bf16 v[48:51], v[16:19], v[20:23], v[8:11]
	ds_read_b128 v[16:19], v124 offset:64
	s_nop 4
	ds_read_b128 v[8:11], v124
	s_waitcnt lgkmcnt(0)
	v_mfma_f32_16x16x32_bf16 v[8:11], v[8:11], v[12:15], 0
	v_fma_f32 v48, -v55, v70, v48
	v_cndmask_b32_e64 v48, v141, v48, s[20:21]
	v_cmp_gt_i32_e64 s[20:21], s88, v67
	v_mfma_f32_16x16x32_bf16 v[44:47], v[16:19], v[20:23], v[8:11]
	ds_read_b128 v[16:19], v125 offset:64
	s_and_b64 s[20:21], s[24:25], s[20:21]
	v_fma_f32 v49, -v55, v71, v49
	s_nop 0
	ds_read_b128 v[8:11], v125
	s_waitcnt lgkmcnt(0)
	v_mfma_f32_16x16x32_bf16 v[8:11], v[8:11], v[12:15], 0
	v_or_b32_e32 v67, 2, v53
	v_cndmask_b32_e64 v49, v141, v49, s[20:21]
	s_and_b64 s[24:25], s[4:5], s[22:23]
	v_mfma_f32_16x16x32_bf16 v[40:43], v[16:19], v[20:23], v[8:11]
	ds_read_b128 v[16:19], v126 offset:64
	v_cmp_gt_i32_e64 s[20:21], s88, v67
	s_and_b64 s[20:21], s[24:25], s[20:21]
	s_nop 0
	ds_read_b128 v[8:11], v126
	s_waitcnt lgkmcnt(0)
	v_mfma_f32_16x16x32_bf16 v[8:11], v[8:11], v[12:15], 0
	v_fma_f32 v50, -v55, v72, v50
	v_or_b32_e32 v53, 3, v53
	v_cndmask_b32_e64 v50, v141, v50, s[20:21]
	v_mfma_f32_16x16x32_bf16 v[36:39], v[16:19], v[20:23], v[8:11]
	ds_read_b128 v[16:19], v127 offset:64
	s_and_b64 s[22:23], s[6:7], s[22:23]
	v_cmp_gt_i32_e64 s[20:21], s88, v53
	s_nop 0
	ds_read_b128 v[8:11], v127
	s_waitcnt lgkmcnt(0)
	v_mfma_f32_16x16x32_bf16 v[8:11], v[8:11], v[12:15], 0
	s_and_b64 s[20:21], s[22:23], s[20:21]
	v_fma_f32 v51, -v55, v73, v51
	v_cndmask_b32_e64 v51, v141, v51, s[20:21]
	v_mfma_f32_16x16x32_bf16 v[32:35], v[16:19], v[20:23], v[8:11]
	s_add_i32 s20, s89, s44
	s_cmp_gt_i32 s20, -1
	v_or_b32_e32 v53, s20, v68
	s_nop 0
	ds_read_b128 v[8:11], v128
	ds_read_b128 v[16:19], v128 offset:64
	s_cselect_b64 s[22:23], -1, 0
	v_cmp_gt_i32_e64 s[20:21], s88, v53
	s_and_b64 s[20:21], s[22:23], s[20:21]
	v_fma_f32 v44, -v55, v74, v44
	v_or_b32_e32 v67, 1, v53
	v_cndmask_b32_e64 v44, v141, v44, s[20:21]
	v_cmp_gt_i32_e64 s[20:21], s88, v67
	s_and_b64 s[20:21], s[22:23], s[20:21]
	v_fma_f32 v45, -v55, v75, v45
	v_or_b32_e32 v67, 2, v53
	v_cndmask_b32_e64 v45, v141, v45, s[20:21]
	v_cmp_gt_i32_e64 s[20:21], s88, v67
	s_and_b64 s[20:21], s[22:23], s[20:21]
	v_fma_f32 v46, -v55, v76, v46
	v_or_b32_e32 v53, 3, v53
	v_cndmask_b32_e64 v46, v141, v46, s[20:21]
	v_cmp_gt_i32_e64 s[20:21], s88, v53
	s_waitcnt lgkmcnt(1)
	v_mfma_f32_16x16x32_bf16 v[8:11], v[8:11], v[12:15], 0
	s_and_b64 s[20:21], s[22:23], s[20:21]
	v_fma_f32 v47, -v55, v77, v47
	v_cndmask_b32_e64 v47, v141, v47, s[20:21]
	s_add_i32 s20, s89, s45
	s_cmp_gt_i32 s20, -1
	v_or_b32_e32 v53, s20, v68
	s_cselect_b64 s[22:23], -1, 0
	v_cmp_gt_i32_e64 s[20:21], s88, v53
	s_waitcnt lgkmcnt(0)
	v_mfma_f32_16x16x32_bf16 v[28:31], v[16:19], v[20:23], v[8:11]
	s_and_b64 s[20:21], s[22:23], s[20:21]
	v_fma_f32 v40, -v55, v78, v40
	v_or_b32_e32 v67, 1, v53
	ds_read_b128 v[8:11], v129
	ds_read_b128 v[16:19], v129 offset:64
	v_cndmask_b32_e64 v40, v141, v40, s[20:21]
	v_cmp_gt_i32_e64 s[20:21], s88, v67
	s_and_b64 s[20:21], s[22:23], s[20:21]
	v_fma_f32 v41, -v55, v79, v41
	v_or_b32_e32 v67, 2, v53
	v_cndmask_b32_e64 v41, v141, v41, s[20:21]
	v_cmp_gt_i32_e64 s[20:21], s88, v67
	s_and_b64 s[20:21], s[22:23], s[20:21]
	v_fma_f32 v42, -v55, v80, v42
	v_or_b32_e32 v53, 3, v53
	v_cndmask_b32_e64 v42, v141, v42, s[20:21]
	v_cmp_gt_i32_e64 s[20:21], s88, v53
	s_and_b64 s[20:21], s[22:23], s[20:21]
	v_fma_f32 v43, -v55, v81, v43
	v_cndmask_b32_e64 v43, v141, v43, s[20:21]
	s_add_i32 s20, s89, s46
	s_cmp_gt_i32 s20, -1
	v_or_b32_e32 v53, s20, v68
	s_waitcnt lgkmcnt(1)
	v_mfma_f32_16x16x32_bf16 v[8:11], v[8:11], v[12:15], 0
	s_cselect_b64 s[22:23], -1, 0
	v_cmp_gt_i32_e64 s[20:21], s88, v53
	s_and_b64 s[20:21], s[22:23], s[20:21]
	v_fma_f32 v36, -v55, v82, v36
	v_or_b32_e32 v67, 1, v53
	v_cndmask_b32_e64 v36, v141, v36, s[20:21]
	v_cmp_gt_i32_e64 s[20:21], s88, v67
	s_and_b64 s[20:21], s[22:23], s[20:21]
	v_fma_f32 v37, -v55, v83, v37
	v_or_b32_e32 v67, 2, v53
	s_waitcnt lgkmcnt(0)
	v_mfma_f32_16x16x32_bf16 v[24:27], v[16:19], v[20:23], v[8:11]
	v_max_f32_e32 v66, 0xf149f2ca, v48
	v_cndmask_b32_e64 v37, v141, v37, s[20:21]
	v_cmp_gt_i32_e64 s[20:21], s88, v67
	ds_read_b128 v[8:11], v130
	ds_read_b128 v[16:19], v130 offset:64
	v_max3_f32 v66, v66, v49, v50
	s_and_b64 s[20:21], s[22:23], s[20:21]
	v_fma_f32 v38, -v55, v84, v38
	v_or_b32_e32 v53, 3, v53
	v_max3_f32 v66, v66, v51, v44
	v_cndmask_b32_e64 v38, v141, v38, s[20:21]
	v_cmp_gt_i32_e64 s[20:21], s88, v53
	v_max3_f32 v66, v66, v45, v46
	s_and_b64 s[20:21], s[22:23], s[20:21]
	v_fma_f32 v39, -v55, v85, v39
	v_max3_f32 v66, v66, v47, v40
	v_cndmask_b32_e64 v39, v141, v39, s[20:21]
	s_add_i32 s20, s89, s47
	v_max3_f32 v66, v66, v41, v42
	v_or_b32_e32 v53, s20, v68
	v_max3_f32 v66, v66, v43, v36
	v_cmp_gt_i32_e64 s[20:21], s88, v53
	v_fma_f32 v32, -v55, v86, v32
	v_max3_f32 v66, v66, v37, v38
	v_cndmask_b32_e64 v67, v141, v32, s[20:21]
	v_max3_f32 v32, v66, v39, v67
	v_or_b32_e32 v66, 1, v53
	s_waitcnt lgkmcnt(1)
	v_mfma_f32_16x16x32_bf16 v[8:11], v[8:11], v[12:15], 0
	v_cmp_gt_i32_e64 s[20:21], s88, v66
	v_fma_f32 v33, -v55, v87, v33
	v_or_b32_e32 v66, 2, v53
	v_cndmask_b32_e64 v33, v141, v33, s[20:21]
	v_cmp_gt_i32_e64 s[20:21], s88, v66
	v_fma_f32 v34, -v55, v88, v34
	v_or_b32_e32 v53, 3, v53
	v_cndmask_b32_e64 v34, v141, v34, s[20:21]
	v_cmp_gt_i32_e64 s[20:21], s88, v53
	v_fma_f32 v35, -v55, v89, v35
	s_waitcnt lgkmcnt(0)
	v_mfma_f32_16x16x32_bf16 v[16:19], v[16:19], v[20:23], v[8:11]
	v_cndmask_b32_e64 v35, v141, v35, s[20:21]
	s_add_i32 s20, s89, s48
	v_or_b32_e32 v53, s20, v68
	ds_read_b128 v[8:11], v131
	v_cmp_gt_i32_e64 s[20:21], s88, v53
	v_fma_f32 v28, -v55, v90, v28
	v_or_b32_e32 v66, 1, v53
	v_cndmask_b32_e64 v28, v141, v28, s[20:21]
	v_cmp_gt_i32_e64 s[20:21], s88, v66
	v_fma_f32 v29, -v55, v91, v29
	v_or_b32_e32 v66, 2, v53
	v_cndmask_b32_e64 v29, v141, v29, s[20:21]
	v_cmp_gt_i32_e64 s[20:21], s88, v66
	v_fma_f32 v30, -v55, v92, v30
	v_or_b32_e32 v53, 3, v53
	v_cndmask_b32_e64 v30, v141, v30, s[20:21]
	v_cmp_gt_i32_e64 s[20:21], s88, v53
	v_fma_f32 v31, -v55, v93, v31
	v_fma_f32 v24, -v55, v94, v24
	v_cndmask_b32_e64 v31, v141, v31, s[20:21]
	s_add_i32 s20, s89, s49
	v_or_b32_e32 v53, s20, v68
	v_cmp_gt_i32_e64 s[20:21], s88, v53
	v_or_b32_e32 v66, 1, v53
	v_fma_f32 v25, -v55, v95, v25
	v_cndmask_b32_e64 v24, v141, v24, s[20:21]
	v_cmp_gt_i32_e64 s[20:21], s88, v66
	v_or_b32_e32 v66, 2, v53
	s_waitcnt lgkmcnt(0)
	v_mfma_f32_16x16x32_bf16 v[142:145], v[8:11], v[12:15], 0
	ds_read_b128 v[12:15], v131 offset:64
	v_cndmask_b32_e64 v25, v141, v25, s[20:21]
	v_cmp_gt_i32_e64 s[20:21], s88, v66
	v_fma_f32 v26, -v55, v96, v26
	v_or_b32_e32 v53, 3, v53
	v_cndmask_b32_e64 v26, v141, v26, s[20:21]
	v_cmp_gt_i32_e64 s[20:21], s88, v53
	v_fma_f32 v27, -v55, v97, v27
	v_fma_f32 v16, -v55, v98, v16
	v_cndmask_b32_e64 v27, v141, v27, s[20:21]
	s_add_i32 s20, s89, s50
	v_or_b32_e32 v53, s20, v68
	v_cmp_gt_i32_e64 s[20:21], s88, v53
	v_or_b32_e32 v66, 1, v53
	v_fma_f32 v17, -v55, v99, v17
	v_cndmask_b32_e64 v16, v141, v16, s[20:21]
	v_cmp_gt_i32_e64 s[20:21], s88, v66
	v_or_b32_e32 v66, 2, v53
	v_fma_f32 v18, -v55, v100, v18
	v_cndmask_b32_e64 v17, v141, v17, s[20:21]
	v_cmp_gt_i32_e64 s[20:21], s88, v66
	s_and_b64 s[20:21], s[8:9], s[20:21]
	v_or_b32_e32 v53, 3, v53
	v_cndmask_b32_e64 v18, v141, v18, s[20:21]
	v_cmp_gt_i32_e64 s[20:21], s88, v53
	s_waitcnt lgkmcnt(0)
	v_mfma_f32_16x16x32_bf16 v[20:23], v[12:15], v[20:23], v[142:145]
	s_and_b64 s[20:21], s[10:11], s[20:21]
	v_fma_f32 v19, -v55, v101, v19
	v_cndmask_b32_e64 v19, v141, v19, s[20:21]
	s_add_i32 s20, s89, s51
	v_or_b32_e32 v53, s20, v68
	v_cmp_gt_i32_e64 s[26:27], s88, v53
	v_max3_f32 v32, v32, v33, v34
	s_and_b64 s[20:21], s[12:13], s[26:27]
	v_fma_f32 v20, -v55, v102, v20
	v_or_b32_e32 v66, 1, v53
	v_max3_f32 v32, v32, v35, v28
	v_cndmask_b32_e64 v20, v141, v20, s[20:21]
	v_cmp_gt_i32_e64 s[20:21], s88, v66
	v_max3_f32 v32, v32, v29, v30
	s_and_b64 s[22:23], s[14:15], s[20:21]
	v_fma_f32 v21, -v55, v103, v21
	v_max3_f32 v32, v32, v31, v24
	v_cndmask_b32_e64 v66, v141, v21, s[22:23]
	v_or_b32_e32 v21, 2, v53
	v_max3_f32 v32, v32, v25, v26
	v_cmp_gt_i32_e64 s[22:23], s88, v21
	v_max3_f32 v32, v32, v27, v16
	s_and_b64 s[24:25], s[16:17], s[22:23]
	v_fma_f32 v21, -v55, v104, v22
	v_or_b32_e32 v22, 3, v53
	v_max3_f32 v32, v32, v17, v18
	v_cndmask_b32_e64 v142, v141, v21, s[24:25]
	v_cmp_gt_i32_e64 s[24:25], s88, v22
	v_max3_f32 v32, v32, v19, v20
	s_and_b64 s[28:29], s[18:19], s[24:25]
	v_fma_f32 v22, -v55, v105, v23
	v_max3_f32 v21, v32, v66, v142
	v_cndmask_b32_e64 v23, v141, v22, s[28:29]
	v_max3_f32 v21, v21, v23, s83
	ds_bpermute_b32 v22, v119, v21
	s_waitcnt lgkmcnt(0)
	v_max_f32_e32 v22, v22, v22
	v_max_f32_e32 v21, v21, v22
	ds_bpermute_b32 v22, v120, v21
	s_waitcnt lgkmcnt(0)
	v_max_f32_e32 v22, v22, v22
	v_max_f32_e32 v32, v21, v22
	v_sub_f32_e32 v22, v49, v32
	v_mul_f32_e32 v22, 0x3fb8aa3b, v22
	v_exp_f32_e32 v49, v22
	v_sub_f32_e32 v22, v50, v32
	v_mul_f32_e32 v22, 0x3fb8aa3b, v22
	v_exp_f32_e32 v50, v22
	v_sub_f32_e32 v22, v51, v32
	v_mul_f32_e32 v22, 0x3fb8aa3b, v22
	v_exp_f32_e32 v51, v22
	v_sub_f32_e32 v22, v44, v32
	v_mul_f32_e32 v22, 0x3fb8aa3b, v22
	v_exp_f32_e32 v44, v22
	v_sub_f32_e32 v22, v45, v32
	v_mul_f32_e32 v22, 0x3fb8aa3b, v22
	v_exp_f32_e32 v45, v22
	v_sub_f32_e32 v22, v46, v32
	v_mul_f32_e32 v22, 0x3fb8aa3b, v22
	v_exp_f32_e32 v46, v22
	v_sub_f32_e32 v22, v47, v32
	v_mul_f32_e32 v22, 0x3fb8aa3b, v22
	v_exp_f32_e32 v47, v22
	v_sub_f32_e32 v22, v40, v32
	v_mul_f32_e32 v22, 0x3fb8aa3b, v22
	v_exp_f32_e32 v53, v22
	v_sub_f32_e32 v22, v41, v32
	v_mul_f32_e32 v22, 0x3fb8aa3b, v22
	v_exp_f32_e32 v143, v22
	v_sub_f32_e32 v22, v42, v32
	v_mul_f32_e32 v22, 0x3fb8aa3b, v22
	v_exp_f32_e32 v144, v22
	v_sub_f32_e32 v22, v43, v32
	v_sub_f32_e32 v21, v48, v32
	v_mul_f32_e32 v22, 0x3fb8aa3b, v22
	v_mul_f32_e32 v21, 0x3fb8aa3b, v21
	v_exp_f32_e32 v145, v22
	v_sub_f32_e32 v22, v36, v32
	v_exp_f32_e32 v48, v21
	v_mul_f32_e32 v22, 0x3fb8aa3b, v22
	v_exp_f32_e32 v146, v22
	v_sub_f32_e32 v22, v37, v32
	v_mul_f32_e32 v22, 0x3fb8aa3b, v22
	v_exp_f32_e32 v147, v22
	v_sub_f32_e32 v22, v38, v32
	v_add_f32_e32 v21, 0, v48
	v_mul_f32_e32 v22, 0x3fb8aa3b, v22
	v_add_f32_e32 v21, v49, v21
	v_exp_f32_e32 v148, v22
	v_sub_f32_e32 v22, v39, v32
	v_add_f32_e32 v21, v50, v21
	v_mul_f32_e32 v22, 0x3fb8aa3b, v22
	v_add_f32_e32 v21, v51, v21
	v_exp_f32_e32 v149, v22
	v_sub_f32_e32 v22, v67, v32
	v_add_f32_e32 v21, v44, v21
	v_mul_f32_e32 v22, 0x3fb8aa3b, v22
	v_add_f32_e32 v21, v45, v21
	v_exp_f32_e32 v67, v22
	v_sub_f32_e32 v22, v33, v32
	v_add_f32_e32 v21, v46, v21
	v_mul_f32_e32 v22, 0x3fb8aa3b, v22
	v_add_f32_e32 v21, v47, v21
	v_exp_f32_e32 v150, v22
	v_sub_f32_e32 v22, v34, v32
	v_add_f32_e32 v21, v53, v21
	v_mul_f32_e32 v22, 0x3fb8aa3b, v22
	v_add_f32_e32 v21, v143, v21
	v_exp_f32_e32 v151, v22
	v_sub_f32_e32 v22, v35, v32
	v_add_f32_e32 v21, v144, v21
	v_mul_f32_e32 v22, 0x3fb8aa3b, v22
	v_add_f32_e32 v21, v145, v21
	v_exp_f32_e32 v35, v22
	v_sub_f32_e32 v22, v28, v32
	v_add_f32_e32 v21, v146, v21
	v_mul_f32_e32 v22, 0x3fb8aa3b, v22
	v_add_f32_e32 v21, v147, v21
	v_exp_f32_e32 v152, v22
	v_sub_f32_e32 v22, v29, v32
	v_add_f32_e32 v21, v148, v21
	v_mul_f32_e32 v22, 0x3fb8aa3b, v22
	v_add_f32_e32 v21, v149, v21
	v_exp_f32_e32 v153, v22
	v_sub_f32_e32 v22, v30, v32
	v_add_f32_e32 v21, v67, v21
	v_mul_f32_e32 v22, 0x3fb8aa3b, v22
	v_add_f32_e32 v21, v150, v21
	v_exp_f32_e32 v154, v22
	v_sub_f32_e32 v22, v31, v32
	v_add_f32_e32 v21, v151, v21
	v_mul_f32_e32 v22, 0x3fb8aa3b, v22
	v_add_f32_e32 v21, v35, v21
	v_exp_f32_e32 v155, v22
	v_add_f32_e32 v21, v152, v21
	v_add_f32_e32 v21, v153, v21
	v_add_f32_e32 v21, v154, v21
	v_add_f32_e32 v22, v155, v21
	v_sub_f32_e32 v21, v24, v32
	v_mul_f32_e32 v21, 0x3fb8aa3b, v21
	v_exp_f32_e32 v21, v21
	v_sub_f32_e32 v17, v17, v32
	v_sub_f32_e32 v16, v16, v32
	v_mul_f32_e32 v17, 0x3fb8aa3b, v17
	v_add_f32_e32 v24, v21, v22
	v_sub_f32_e32 v22, v25, v32
	v_sub_f32_e32 v25, v26, v32
	v_mul_f32_e32 v22, 0x3fb8aa3b, v22
	v_mul_f32_e32 v25, 0x3fb8aa3b, v25
	v_exp_f32_e32 v22, v22
	v_exp_f32_e32 v156, v25
	v_sub_f32_e32 v25, v27, v32
	v_mul_f32_e32 v25, 0x3fb8aa3b, v25
	v_exp_f32_e32 v157, v25
	v_mul_f32_e32 v16, 0x3fb8aa3b, v16
	v_exp_f32_e32 v159, v17
	v_sub_f32_e32 v17, v18, v32
	v_exp_f32_e32 v158, v16
	v_mul_f32_e32 v17, 0x3fb8aa3b, v17
	v_add_f32_e32 v24, v22, v24
	v_exp_f32_e32 v160, v17
	v_sub_f32_e32 v17, v19, v32
	v_add_f32_e32 v24, v156, v24
	v_mul_f32_e32 v17, 0x3fb8aa3b, v17
	v_add_f32_e32 v24, v157, v24
	v_exp_f32_e32 v161, v17
	v_add_f32_e32 v16, v158, v24
	v_add_f32_e32 v16, v159, v16
	v_add_f32_e32 v16, v160, v16
	v_add_f32_e32 v17, v161, v16
	v_sub_f32_e32 v16, v20, v32
	v_mul_f32_e32 v16, 0x3fb8aa3b, v16
	v_exp_f32_e32 v16, v16
	v_cvt_pk_bf16_f32 v26, v44, v45
	v_cvt_pk_bf16_f32 v27, v46, v47
	v_cvt_pk_bf16_f32 v25, v50, v51
	v_add_f32_e32 v18, v16, v17
	v_sub_f32_e32 v17, v66, v32
	v_mul_f32_e32 v17, 0x3fb8aa3b, v17
	v_exp_f32_e32 v17, v17
	s_nop 0
	v_add_f32_e32 v19, v17, v18
	v_sub_f32_e32 v18, v142, v32
	v_mul_f32_e32 v18, 0x3fb8aa3b, v18
	v_exp_f32_e32 v18, v18
	s_nop 0
	v_add_f32_e32 v20, v18, v19
	v_sub_f32_e32 v19, v23, v32
	v_mul_f32_e32 v19, 0x3fb8aa3b, v19
	v_exp_f32_e32 v19, v19
	s_nop 0
	v_add_f32_e32 v23, v19, v20
	v_sub_f32_e32 v20, 0xf149f2ca, v32
	v_mul_f32_e32 v20, 0x3fb8aa3b, v20
	v_exp_f32_e32 v20, v20
	s_nop 0
	v_add_f32_e32 v23, v20, v23
	v_add_f32_e32 v23, v20, v23
	v_add_f32_e32 v23, v20, v23
	v_add_f32_e32 v23, v20, v23
	ds_bpermute_b32 v24, v119, v23
	s_waitcnt lgkmcnt(0)
	v_add_f32_e32 v33, v23, v24
	v_add_u32_e32 v23, v107, v106
	v_add_u32_e32 v23, 0xe000, v23
	ds_read2_b64 v[28:31], v23 offset0:32 offset1:36
	v_add_u32_e32 v23, v107, v108
	v_add_u32_e32 v23, 0xe000, v23
	ds_read2_b64 v[36:39], v23 offset0:32 offset1:36
	v_add_u32_e32 v23, v107, v109
	v_add_u32_e32 v23, 0xe000, v23
	ds_read2_b64 v[40:43], v23 offset0:32 offset1:36
	v_add_u32_e32 v23, v107, v110
	v_add_u32_e32 v23, 0xe000, v23
	ds_read2_b64 v[44:47], v23 offset0:32 offset1:36
	v_add_u32_e32 v23, v111, v106
	v_add_u32_e32 v23, 0xe000, v23
	v_cvt_pk_bf16_f32 v24, v48, v49
	ds_read2_b64 v[48:51], v23 offset0:32 offset1:36
	v_add_u32_e32 v23, v111, v108
	s_waitcnt lgkmcnt(4)
	v_mfma_f32_16x16x32_bf16 v[28:31], v[28:31], v[24:27], 0
	v_add_u32_e32 v23, 0xe000, v23
	ds_bpermute_b32 v34, v120, v33
	s_waitcnt lgkmcnt(0)
	v_add_f32_e32 v33, v33, v34
	v_mfma_f32_16x16x32_bf16 v[36:39], v[36:39], v[24:27], 0
	v_rcp_f32_e32 v34, v33
	v_mfma_f32_16x16x32_bf16 v[40:43], v[40:43], v[24:27], 0
	v_mfma_f32_16x16x32_bf16 v[24:27], v[44:47], v[24:27], 0
	v_cvt_pk_bf16_f32 v44, v53, v143
	v_cvt_pk_bf16_f32 v45, v144, v145
	v_cvt_pk_bf16_f32 v46, v146, v147
	v_cvt_pk_bf16_f32 v47, v148, v149
	s_nop 1
	v_mfma_f32_16x16x32_bf16 v[28:31], v[48:51], v[44:47], v[28:31]
	ds_read2_b64 v[48:51], v23 offset0:32 offset1:36
	v_add_u32_e32 v23, v111, v109
	v_add_u32_e32 v23, 0xe000, v23
	s_waitcnt lgkmcnt(0)
	v_mfma_f32_16x16x32_bf16 v[36:39], v[48:51], v[44:47], v[36:39]
	ds_read2_b64 v[48:51], v23 offset0:32 offset1:36
	v_add_u32_e32 v23, v111, v110
	v_add_u32_e32 v23, 0xe000, v23
	s_waitcnt lgkmcnt(0)
	v_mfma_f32_16x16x32_bf16 v[40:43], v[48:51], v[44:47], v[40:43]
	ds_read2_b64 v[48:51], v23 offset0:32 offset1:36
	v_add_u32_e32 v23, v112, v106
	v_add_u32_e32 v23, 0xe000, v23
	s_waitcnt lgkmcnt(0)
	v_mfma_f32_16x16x32_bf16 v[24:27], v[48:51], v[44:47], v[24:27]
	ds_read2_b64 v[48:51], v23 offset0:32 offset1:36
	v_add_u32_e32 v23, v112, v108
	v_cvt_pk_bf16_f32 v44, v67, v150
	v_cvt_pk_bf16_f32 v45, v151, v35
	v_cvt_pk_bf16_f32 v46, v152, v153
	v_cvt_pk_bf16_f32 v47, v154, v155
	v_add_u32_e32 v23, 0xe000, v23
	s_waitcnt lgkmcnt(0)
	v_mfma_f32_16x16x32_bf16 v[28:31], v[48:51], v[44:47], v[28:31]
	ds_read2_b64 v[48:51], v23 offset0:32 offset1:36
	v_add_u32_e32 v23, v112, v109
	v_add_u32_e32 v23, 0xe000, v23
	s_waitcnt lgkmcnt(0)
	v_mfma_f32_16x16x32_bf16 v[36:39], v[48:51], v[44:47], v[36:39]
	ds_read2_b64 v[48:51], v23 offset0:32 offset1:36
	v_add_u32_e32 v23, v112, v110
	v_add_u32_e32 v23, 0xe000, v23
	s_waitcnt lgkmcnt(0)
	v_mfma_f32_16x16x32_bf16 v[40:43], v[48:51], v[44:47], v[40:43]
	ds_read2_b64 v[48:51], v23 offset0:32 offset1:36
	s_waitcnt lgkmcnt(0)
	v_mfma_f32_16x16x32_bf16 v[24:27], v[48:51], v[44:47], v[24:27]
	v_cvt_pk_bf16_f32 v44, v21, v22
	v_add_u32_e32 v21, v113, v106
	v_add_u32_e32 v21, 0xe000, v21
	ds_read2_b64 v[48:51], v21 offset0:32 offset1:36
	v_add_u32_e32 v21, v113, v108
	v_cvt_pk_bf16_f32 v45, v156, v157
	v_cvt_pk_bf16_f32 v46, v158, v159
	v_cvt_pk_bf16_f32 v47, v160, v161
	v_add_u32_e32 v21, 0xe000, v21
	s_waitcnt lgkmcnt(0)
	v_mfma_f32_16x16x32_bf16 v[28:31], v[48:51], v[44:47], v[28:31]
	ds_read2_b64 v[48:51], v21 offset0:32 offset1:36
	v_add_u32_e32 v21, v113, v109
	v_add_u32_e32 v21, 0xe000, v21
	s_waitcnt lgkmcnt(0)
	v_mfma_f32_16x16x32_bf16 v[36:39], v[48:51], v[44:47], v[36:39]
	ds_read2_b64 v[48:51], v21 offset0:32 offset1:36
	v_add_u32_e32 v21, v113, v110
	v_add_u32_e32 v21, 0xe000, v21
	s_waitcnt lgkmcnt(0)
	v_mfma_f32_16x16x32_bf16 v[40:43], v[48:51], v[44:47], v[40:43]
	ds_read2_b64 v[48:51], v21 offset0:32 offset1:36
	s_waitcnt lgkmcnt(0)
	v_mfma_f32_16x16x32_bf16 v[44:47], v[48:51], v[44:47], v[24:27]
	v_cvt_pk_bf16_f32 v48, v16, v17
	v_add_u32_e32 v16, v114, v106
	v_add_u32_e32 v16, 0xe000, v16
	v_cvt_pk_bf16_f32 v49, v18, v19
	ds_read2_b64 v[16:19], v16 offset0:32 offset1:36
	v_cvt_pk_bf16_f32 v50, v20, v20
	v_add_u32_e32 v20, v114, v108
	v_add_u32_e32 v20, 0xe000, v20
	ds_read2_b64 v[20:23], v20 offset0:32 offset1:36
	v_add_u32_e32 v24, v114, v109
	v_mov_b32_e32 v51, v50
	v_add_u32_e32 v24, 0xe000, v24
	ds_read2_b64 v[24:27], v24 offset0:32 offset1:36
	s_waitcnt lgkmcnt(2)
	v_mfma_f32_16x16x32_bf16 v[142:145], v[16:19], v[48:51], v[28:31]
	s_nop 2
	v_add_u32_e32 v28, v114, v110
	v_add_u32_e32 v28, 0xe000, v28
	ds_read2_b64 v[28:31], v28 offset0:32 offset1:36
	s_waitcnt lgkmcnt(2)
	v_mfma_f32_16x16x32_bf16 v[36:39], v[20:23], v[48:51], v[36:39]
	v_mul_f32_e64 v66, v34, v144
	v_mul_f32_e64 v67, v34, v145
	s_waitcnt lgkmcnt(1)
	v_mfma_f32_16x16x32_bf16 v[40:43], v[24:27], v[48:51], v[40:43]
	s_waitcnt lgkmcnt(0)
	v_mfma_f32_16x16x32_bf16 v[44:47], v[28:31], v[48:51], v[44:47]
	s_nop 1
	v_mul_f32_e64 v36, v34, v36
	v_mul_f32_e64 v37, v34, v37
	v_pk_mul_f32 v[38:39], v[34:35], v[38:39] op_sel_hi:[0,1]
	v_mad_i64_i32 v[48:49], s[28:29], v52, s82, v[64:65]
	v_cvt_pk_bf16_f32 v36, v36, v37
	v_cvt_pk_bf16_f32 v37, v38, v39
	global_store_dwordx2 v[48:49], v[36:37], off offset:32
	v_pk_mul_f32 v[36:37], v[34:35], v[40:41] op_sel_hi:[0,1]
	v_pk_mul_f32 v[38:39], v[34:35], v[42:43] op_sel_hi:[0,1]
	v_cvt_pk_bf16_f32 v36, v36, v37
	v_cvt_pk_bf16_f32 v37, v38, v39
	v_pk_mul_f32 v[50:51], v[34:35], v[142:143] op_sel_hi:[0,1]
	global_store_dwordx2 v[48:49], v[36:37], off offset:64
	v_pk_mul_f32 v[36:37], v[34:35], v[44:45] op_sel_hi:[0,1]
	v_pk_mul_f32 v[34:35], v[34:35], v[46:47] op_sel_hi:[0,1]
	v_cvt_pk_bf16_f32 v50, v50, v51
	v_cvt_pk_bf16_f32 v51, v66, v67
	v_cvt_pk_bf16_f32 v36, v36, v37
	v_cvt_pk_bf16_f32 v37, v34, v35
	global_store_dwordx2 v[48:49], v[50:51], off
	global_store_dwordx2 v[48:49], v[36:37], off offset:96
	s_and_saveexec_b64 s[28:29], vcc
	s_cbranch_execz .LBB0_527
	v_log_f32_e32 v33, v33
	v_ashrrev_i32_e32 v53, 31, v52
	v_lshlrev_b64 v[34:35], 5, v[52:53]
	v_lshl_add_u64 v[34:35], s[40:41], 0, v[34:35]
	v_fmac_f32_e32 v32, 0x3f317218, v33
	global_store_dword v[34:35], v32, off
.LBB0_527:
	s_or_b64 exec, exec, s[28:29]
	s_waitcnt vmcnt(21)
	v_mfma_f32_16x16x32_bf16 v[8:11], v[8:11], v[4:7], 0
	v_add_u32_e32 v32, s51, v54
	v_lshlrev_b32_e32 v32, s90, v32
	v_add_u32_e32 v66, s91, v32
	s_waitcnt vmcnt(20)
	v_mfma_f32_16x16x32_bf16 v[8:11], v[12:15], v[0:3], v[8:11]
	ds_read_b128 v[12:15], v132
	ds_read_b128 v[32:35], v132 offset:64
	v_mul_f32_e32 v182, v55, v70
	v_mul_f32_e32 v177, v55, v71
	v_mul_f32_e32 v176, v55, v72
	v_mul_f32_e32 v175, v55, v73
	v_mul_f32_e32 v174, v55, v74
	v_mul_f32_e32 v173, v55, v75
	s_waitcnt lgkmcnt(1)
	v_mfma_f32_16x16x32_bf16 v[12:15], v[12:15], v[4:7], 0
	v_mul_f32_e32 v172, v55, v76
	v_mul_f32_e32 v169, v55, v77
	v_mul_f32_e32 v168, v55, v78
	v_mul_f32_e32 v167, v55, v79
	v_mul_f32_e32 v166, v55, v80
	v_mul_f32_e32 v165, v55, v81
	v_mul_f32_e32 v164, v55, v82
	v_mul_f32_e32 v163, v55, v83
	v_mul_f32_e32 v162, v55, v84
	v_mul_f32_e32 v161, v55, v85
	v_mul_f32_e32 v160, v55, v86
	v_mul_f32_e32 v159, v55, v87
	v_mul_f32_e32 v158, v55, v88
	v_mul_f32_e32 v157, v55, v89
	v_mul_f32_e32 v156, v55, v90
	v_mul_f32_e32 v155, v55, v91
	v_mul_f32_e32 v154, v55, v92
	v_mul_f32_e32 v153, v55, v93
	v_mul_f32_e32 v152, v55, v94
	v_mul_f32_e32 v151, v55, v95
	v_mul_f32_e32 v150, v55, v96
	v_mul_f32_e32 v149, v55, v97
	v_mul_f32_e32 v148, v55, v98
	v_mul_f32_e32 v147, v55, v99
	v_mul_f32_e32 v146, v55, v100
	v_mul_f32_e32 v145, v55, v101
	v_mul_f32_e32 v144, v55, v102
	v_mul_f32_e32 v143, v55, v103
	v_mul_f32_e32 v142, v55, v104
	v_mul_f32_e32 v67, v55, v105
	s_waitcnt lgkmcnt(0)
	v_mfma_f32_16x16x32_bf16 v[52:55], v[32:35], v[0:3], v[12:15]
	ds_read_b128 v[32:35], v133 offset:64
	s_and_b64 s[20:21], s[2:3], s[20:21]
	s_and_b64 s[26:27], s[0:1], s[26:27]
	ds_read_b128 v[12:15], v133
	s_waitcnt lgkmcnt(0)
	v_mfma_f32_16x16x32_bf16 v[12:15], v[12:15], v[4:7], 0
	ds_read_b128 v[178:181], v138 offset:64
	v_mfma_f32_16x16x32_bf16 v[48:51], v[32:35], v[0:3], v[12:15]
	ds_read_b128 v[32:35], v134 offset:64
	s_nop 4
	ds_read_b128 v[12:15], v134
	s_waitcnt lgkmcnt(0)
	v_mfma_f32_16x16x32_bf16 v[12:15], v[12:15], v[4:7], 0
	v_sub_f32_e32 v48, v48, v168
	v_sub_f32_e32 v49, v49, v167
	v_sub_f32_e32 v50, v50, v166
	v_mfma_f32_16x16x32_bf16 v[44:47], v[32:35], v[0:3], v[12:15]
	ds_read_b128 v[32:35], v135 offset:64
	v_sub_f32_e32 v51, v51, v165
	s_nop 1
	ds_read_b128 v[12:15], v135
	s_waitcnt lgkmcnt(0)
	v_mfma_f32_16x16x32_bf16 v[12:15], v[12:15], v[4:7], 0
	s_nop 0
	v_sub_f32_e32 v44, v44, v164
	v_sub_f32_e32 v45, v45, v163
	v_sub_f32_e32 v46, v46, v162
	v_mfma_f32_16x16x32_bf16 v[40:43], v[32:35], v[0:3], v[12:15]
	ds_read_b128 v[32:35], v136 offset:64
	v_sub_f32_e32 v47, v47, v161
	s_nop 0
	ds_read_b128 v[12:15], v136
	s_waitcnt lgkmcnt(0)
	v_mfma_f32_16x16x32_bf16 v[12:15], v[12:15], v[4:7], 0
	s_nop 1
	v_sub_f32_e32 v40, v40, v160
	v_sub_f32_e32 v41, v41, v159
	v_sub_f32_e32 v42, v42, v158
	v_mfma_f32_16x16x32_bf16 v[36:39], v[32:35], v[0:3], v[12:15]
	ds_read_b128 v[32:35], v137 offset:64
	v_sub_f32_e32 v43, v43, v157
	s_nop 0
	ds_read_b128 v[12:15], v137
	s_waitcnt lgkmcnt(0)
	v_mfma_f32_16x16x32_bf16 v[12:15], v[12:15], v[4:7], 0
	s_nop 1
	v_sub_f32_e32 v36, v36, v156
	v_sub_f32_e32 v37, v37, v155
	v_sub_f32_e32 v38, v38, v154
	v_mfma_f32_16x16x32_bf16 v[32:35], v[32:35], v[0:3], v[12:15]
	v_sub_f32_e32 v39, v39, v153
	s_nop 1
	ds_read_b128 v[12:15], v138
	s_waitcnt lgkmcnt(0)
	v_mfma_f32_16x16x32_bf16 v[12:15], v[12:15], v[4:7], 0
	s_nop 1
	v_sub_f32_e32 v32, v32, v152
	v_sub_f32_e32 v33, v33, v151
	v_sub_f32_e32 v34, v34, v150
	v_mfma_f32_16x16x32_bf16 v[12:15], v[178:181], v[0:3], v[12:15]
	ds_read_b128 v[178:181], v139
	v_sub_f32_e32 v35, v35, v149
	s_waitcnt lgkmcnt(0)
	v_mfma_f32_16x16x32_bf16 v[4:7], v[178:181], v[4:7], 0
	ds_read_b128 v[178:181], v139 offset:64
	s_nop 2
	v_sub_f32_e32 v12, v12, v148
	v_sub_f32_e32 v13, v13, v147
	s_waitcnt lgkmcnt(0)
	v_mfma_f32_16x16x32_bf16 v[0:3], v[178:181], v[0:3], v[4:7]
	s_nop 2
	v_sub_f32_e32 v6, v9, v177
	v_cndmask_b32_e64 v6, v141, v6, s[20:21]
	s_and_b64 s[20:21], s[4:5], s[22:23]
	v_sub_f32_e32 v7, v10, v176
	v_sub_f32_e32 v4, v8, v182
	v_cndmask_b32_e64 v7, v141, v7, s[20:21]
	s_and_b64 s[20:21], s[6:7], s[24:25]
	v_sub_f32_e32 v8, v11, v175
	v_cndmask_b32_e64 v8, v141, v8, s[20:21]
	s_add_i32 s20, s89, s52
	v_or_b32_e32 v9, s20, v68
	v_cmp_gt_i32_e64 s[20:21], s88, v9
	v_sub_f32_e32 v10, v52, v174
	v_or_b32_e32 v11, 1, v9
	v_cndmask_b32_e64 v10, v141, v10, s[20:21]
	v_cmp_gt_i32_e64 s[20:21], s88, v11
	v_sub_f32_e32 v11, v53, v173
	v_or_b32_e32 v52, 2, v9
	v_cndmask_b32_e64 v11, v141, v11, s[20:21]
	v_cmp_gt_i32_e64 s[20:21], s88, v52
	v_sub_f32_e32 v52, v54, v172
	v_or_b32_e32 v9, 3, v9
	v_cndmask_b32_e64 v52, v141, v52, s[20:21]
	v_cmp_gt_i32_e64 s[20:21], s88, v9
	v_sub_f32_e32 v9, v55, v169
	v_cndmask_b32_e64 v4, v141, v4, s[26:27]
	v_cndmask_b32_e64 v9, v141, v9, s[20:21]
	s_add_i32 s20, s89, s53
	v_or_b32_e32 v53, s20, v68
	v_cmp_gt_i32_e64 s[20:21], s88, v53
	v_or_b32_e32 v54, 1, v53
	v_max_f32_e32 v5, 0xf149f2ca, v4
	v_cndmask_b32_e64 v48, v141, v48, s[20:21]
	v_cmp_gt_i32_e64 s[20:21], s88, v54
	v_or_b32_e32 v54, 2, v53
	v_or_b32_e32 v53, 3, v53
	v_cndmask_b32_e64 v49, v141, v49, s[20:21]
	v_cmp_gt_i32_e64 s[20:21], s88, v54
	v_max3_f32 v5, v5, v6, v7
	v_max3_f32 v5, v5, v8, v10
	v_cndmask_b32_e64 v50, v141, v50, s[20:21]
	v_cmp_gt_i32_e64 s[20:21], s88, v53
	v_max3_f32 v5, v5, v11, v52
	v_max3_f32 v5, v5, v9, v48
	v_cndmask_b32_e64 v51, v141, v51, s[20:21]
	s_add_i32 s20, s89, s60
	v_or_b32_e32 v53, s20, v68
	v_cmp_gt_i32_e64 s[20:21], s88, v53
	v_or_b32_e32 v54, 1, v53
	v_max3_f32 v5, v5, v49, v50
	v_cndmask_b32_e64 v44, v141, v44, s[20:21]
	v_cmp_gt_i32_e64 s[20:21], s88, v54
	v_or_b32_e32 v54, 2, v53
	v_or_b32_e32 v53, 3, v53
	v_cndmask_b32_e64 v45, v141, v45, s[20:21]
	v_cmp_gt_i32_e64 s[20:21], s88, v54
	v_max3_f32 v5, v5, v51, v44
	v_sub_f32_e32 v14, v14, v146
	v_cndmask_b32_e64 v46, v141, v46, s[20:21]
	v_cmp_gt_i32_e64 s[20:21], s88, v53
	v_max3_f32 v5, v5, v45, v46
	v_sub_f32_e32 v15, v15, v145
	v_cndmask_b32_e64 v47, v141, v47, s[20:21]
	s_add_i32 s20, s89, s61
	v_or_b32_e32 v53, s20, v68
	v_cmp_gt_i32_e64 s[20:21], s88, v53
	v_or_b32_e32 v54, 1, v53
	v_sub_f32_e32 v0, v0, v144
	v_cndmask_b32_e64 v40, v141, v40, s[20:21]
	v_cmp_gt_i32_e64 s[20:21], s88, v54
	v_or_b32_e32 v54, 2, v53
	v_or_b32_e32 v53, 3, v53
	v_cndmask_b32_e64 v41, v141, v41, s[20:21]
	v_cmp_gt_i32_e64 s[20:21], s88, v54
	v_max3_f32 v5, v5, v47, v40
	v_sub_f32_e32 v1, v1, v143
	v_cndmask_b32_e64 v42, v141, v42, s[20:21]
	v_cmp_gt_i32_e64 s[20:21], s88, v53
	v_max3_f32 v5, v5, v41, v42
	v_sub_f32_e32 v2, v2, v142
	v_cndmask_b32_e64 v43, v141, v43, s[20:21]
	s_add_i32 s20, s89, s74
	v_or_b32_e32 v53, s20, v68
	v_cmp_gt_i32_e64 s[20:21], s88, v53
	v_or_b32_e32 v54, 1, v53
	v_sub_f32_e32 v3, v3, v67
	v_cndmask_b32_e64 v36, v141, v36, s[20:21]
	v_cmp_gt_i32_e64 s[20:21], s88, v54
	v_or_b32_e32 v54, 2, v53
	v_or_b32_e32 v53, 3, v53
	v_cndmask_b32_e64 v37, v141, v37, s[20:21]
	v_cmp_gt_i32_e64 s[20:21], s88, v54
	v_max3_f32 v5, v5, v43, v36
	s_nop 0
	v_cndmask_b32_e64 v38, v141, v38, s[20:21]
	v_cmp_gt_i32_e64 s[20:21], s88, v53
	v_max3_f32 v5, v5, v37, v38
	s_nop 0
	v_cndmask_b32_e64 v39, v141, v39, s[20:21]
	s_add_i32 s20, s89, s75
	v_or_b32_e32 v53, s20, v68
	v_cmp_gt_i32_e64 s[20:21], s88, v53
	v_or_b32_e32 v54, 1, v53
	s_nop 0
	v_cndmask_b32_e64 v32, v141, v32, s[20:21]
	v_cmp_gt_i32_e64 s[20:21], s88, v54
	v_or_b32_e32 v54, 2, v53
	v_or_b32_e32 v53, 3, v53
	v_cndmask_b32_e64 v33, v141, v33, s[20:21]
	v_cmp_gt_i32_e64 s[20:21], s88, v54
	v_max3_f32 v5, v5, v39, v32
	s_nop 0
	v_cndmask_b32_e64 v34, v141, v34, s[20:21]
	v_cmp_gt_i32_e64 s[20:21], s88, v53
	v_max3_f32 v5, v5, v33, v34
	s_nop 0
	v_cndmask_b32_e64 v35, v141, v35, s[20:21]
	s_add_i32 s20, s89, s76
	v_or_b32_e32 v53, s20, v68
	v_cmp_gt_i32_e64 s[20:21], s88, v53
	v_or_b32_e32 v54, 1, v53
	s_add_i32 s89, s89, s77
	v_cndmask_b32_e64 v12, v141, v12, s[20:21]
	v_cmp_gt_i32_e64 s[20:21], s88, v54
	v_or_b32_e32 v54, 2, v53
	v_or_b32_e32 v53, 3, v53
	v_cndmask_b32_e64 v13, v141, v13, s[20:21]
	v_cmp_gt_i32_e64 s[20:21], s88, v54
	s_and_b64 s[20:21], s[8:9], s[20:21]
	v_max3_f32 v5, v5, v35, v12
	v_cndmask_b32_e64 v14, v141, v14, s[20:21]
	v_cmp_gt_i32_e64 s[20:21], s88, v53
	s_and_b64 s[20:21], s[10:11], s[20:21]
	v_or_b32_e32 v53, s89, v68
	v_cndmask_b32_e64 v15, v141, v15, s[20:21]
	v_cmp_gt_i32_e64 s[20:21], s88, v53
	s_and_b64 s[20:21], s[12:13], s[20:21]
	v_max3_f32 v5, v5, v13, v14
	v_cndmask_b32_e64 v54, v141, v0, s[20:21]
	v_max3_f32 v0, v5, v15, v54
	v_or_b32_e32 v5, 1, v53
	v_cmp_gt_i32_e64 s[20:21], s88, v5
	s_and_b64 s[20:21], s[14:15], s[20:21]
	v_or_b32_e32 v5, 2, v53
	v_cndmask_b32_e64 v1, v141, v1, s[20:21]
	v_cmp_gt_i32_e64 s[20:21], s88, v5
	s_and_b64 s[20:21], s[16:17], s[20:21]
	v_or_b32_e32 v5, 3, v53
	v_cndmask_b32_e64 v2, v141, v2, s[20:21]
	v_cmp_gt_i32_e64 s[20:21], s88, v5
	s_and_b64 s[20:21], s[18:19], s[20:21]
	v_max3_f32 v0, v0, v1, v2
	v_cndmask_b32_e64 v5, v141, v3, s[20:21]
	v_max3_f32 v0, v0, v5, s83
	ds_bpermute_b32 v3, v119, v0
	s_waitcnt lgkmcnt(0)
	v_max_f32_e32 v3, v3, v3
	v_max_f32_e32 v0, v0, v3
	ds_bpermute_b32 v3, v120, v0
	s_waitcnt lgkmcnt(0)
	v_max_f32_e32 v3, v3, v3
	v_max_f32_e32 v0, v0, v3
	v_sub_f32_e32 v3, v4, v0
	v_mul_f32_e32 v3, 0x3fb8aa3b, v3
	v_sub_f32_e32 v6, v6, v0
	v_exp_f32_e32 v4, v3
	v_mul_f32_e32 v6, 0x3fb8aa3b, v6
	v_sub_f32_e32 v7, v7, v0
	v_exp_f32_e32 v6, v6
	v_mul_f32_e32 v7, 0x3fb8aa3b, v7
	v_sub_f32_e32 v8, v8, v0
	v_exp_f32_e32 v7, v7
	v_mul_f32_e32 v8, 0x3fb8aa3b, v8
	v_sub_f32_e32 v10, v10, v0
	v_exp_f32_e32 v8, v8
	v_mul_f32_e32 v10, 0x3fb8aa3b, v10
	v_sub_f32_e32 v11, v11, v0
	v_add_f32_e32 v3, 0, v4
	v_exp_f32_e32 v10, v10
	v_mul_f32_e32 v11, 0x3fb8aa3b, v11
	v_sub_f32_e32 v52, v52, v0
	v_add_f32_e32 v3, v6, v3
	v_exp_f32_e32 v11, v11
	v_mul_f32_e32 v52, 0x3fb8aa3b, v52
	v_sub_f32_e32 v9, v9, v0
	v_add_f32_e32 v3, v7, v3
	v_exp_f32_e32 v52, v52
	v_mul_f32_e32 v9, 0x3fb8aa3b, v9
	v_sub_f32_e32 v48, v48, v0
	v_add_f32_e32 v3, v8, v3
	v_exp_f32_e32 v9, v9
	v_mul_f32_e32 v48, 0x3fb8aa3b, v48
	v_sub_f32_e32 v49, v49, v0
	v_add_f32_e32 v3, v10, v3
	v_exp_f32_e32 v48, v48
	v_mul_f32_e32 v49, 0x3fb8aa3b, v49
	v_sub_f32_e32 v50, v50, v0
	v_add_f32_e32 v3, v11, v3
	v_exp_f32_e32 v49, v49
	v_mul_f32_e32 v50, 0x3fb8aa3b, v50
	v_sub_f32_e32 v51, v51, v0
	v_add_f32_e32 v3, v52, v3
	v_exp_f32_e32 v50, v50
	v_mul_f32_e32 v51, 0x3fb8aa3b, v51
	v_sub_f32_e32 v44, v44, v0
	v_add_f32_e32 v3, v9, v3
	v_exp_f32_e32 v51, v51
	v_mul_f32_e32 v44, 0x3fb8aa3b, v44
	v_sub_f32_e32 v45, v45, v0
	v_add_f32_e32 v3, v48, v3
	v_exp_f32_e32 v44, v44
	v_mul_f32_e32 v45, 0x3fb8aa3b, v45
	v_sub_f32_e32 v46, v46, v0
	v_add_f32_e32 v3, v49, v3
	v_exp_f32_e32 v45, v45
	v_mul_f32_e32 v46, 0x3fb8aa3b, v46
	v_sub_f32_e32 v47, v47, v0
	v_add_f32_e32 v3, v50, v3
	v_exp_f32_e32 v46, v46
	v_mul_f32_e32 v47, 0x3fb8aa3b, v47
	v_sub_f32_e32 v40, v40, v0
	v_add_f32_e32 v3, v51, v3
	v_exp_f32_e32 v47, v47
	v_mul_f32_e32 v40, 0x3fb8aa3b, v40
	v_sub_f32_e32 v41, v41, v0
	v_add_f32_e32 v3, v44, v3
	v_exp_f32_e32 v40, v40
	v_mul_f32_e32 v41, 0x3fb8aa3b, v41
	v_sub_f32_e32 v42, v42, v0
	v_add_f32_e32 v3, v45, v3
	v_exp_f32_e32 v41, v41
	v_mul_f32_e32 v42, 0x3fb8aa3b, v42
	v_sub_f32_e32 v43, v43, v0
	v_add_f32_e32 v3, v46, v3
	v_exp_f32_e32 v42, v42
	v_mul_f32_e32 v43, 0x3fb8aa3b, v43
	v_sub_f32_e32 v36, v36, v0
	v_add_f32_e32 v3, v47, v3
	v_exp_f32_e32 v43, v43
	v_mul_f32_e32 v36, 0x3fb8aa3b, v36
	v_sub_f32_e32 v37, v37, v0
	v_add_f32_e32 v3, v40, v3
	v_exp_f32_e32 v36, v36
	v_mul_f32_e32 v37, 0x3fb8aa3b, v37
	v_sub_f32_e32 v38, v38, v0
	v_add_f32_e32 v3, v41, v3
	v_exp_f32_e32 v37, v37
	v_mul_f32_e32 v38, 0x3fb8aa3b, v38
	v_sub_f32_e32 v39, v39, v0
	v_add_f32_e32 v3, v42, v3
	v_exp_f32_e32 v38, v38
	v_mul_f32_e32 v39, 0x3fb8aa3b, v39
	v_sub_f32_e32 v32, v32, v0
	v_add_f32_e32 v3, v43, v3
	v_exp_f32_e32 v39, v39
	v_mul_f32_e32 v32, 0x3fb8aa3b, v32
	v_sub_f32_e32 v33, v33, v0
	v_sub_f32_e32 v12, v12, v0
	v_add_f32_e32 v3, v36, v3
	v_exp_f32_e32 v32, v32
	v_mul_f32_e32 v33, 0x3fb8aa3b, v33
	v_sub_f32_e32 v34, v34, v0
	v_mul_f32_e32 v12, 0x3fb8aa3b, v12
	v_add_f32_e32 v3, v37, v3
	v_exp_f32_e32 v33, v33
	v_mul_f32_e32 v34, 0x3fb8aa3b, v34
	v_sub_f32_e32 v35, v35, v0
	v_exp_f32_e32 v53, v12
	v_sub_f32_e32 v12, v13, v0
	v_add_f32_e32 v3, v38, v3
	v_exp_f32_e32 v34, v34
	v_mul_f32_e32 v35, 0x3fb8aa3b, v35
	v_mul_f32_e32 v12, 0x3fb8aa3b, v12
	v_add_f32_e32 v3, v39, v3
	v_exp_f32_e32 v35, v35
	v_exp_f32_e32 v55, v12
	v_sub_f32_e32 v12, v14, v0
	v_add_f32_e32 v3, v32, v3
	v_mul_f32_e32 v12, 0x3fb8aa3b, v12
	v_add_f32_e32 v3, v33, v3
	v_exp_f32_e32 v67, v12
	v_sub_f32_e32 v12, v15, v0
	v_sub_f32_e32 v2, v2, v0
	v_add_f32_e32 v3, v34, v3
	v_mul_f32_e32 v12, 0x3fb8aa3b, v12
	v_mul_f32_e32 v2, 0x3fb8aa3b, v2
	v_add_f32_e32 v3, v35, v3
	v_exp_f32_e32 v142, v12
	v_exp_f32_e32 v143, v2
	v_sub_f32_e32 v2, v5, v0
	v_cvt_pk_bf16_f32 v4, v4, v6
	v_cvt_pk_bf16_f32 v5, v7, v8
	v_cvt_pk_bf16_f32 v6, v10, v11
	v_cvt_pk_bf16_f32 v7, v52, v9
	v_add_f32_e32 v3, v53, v3
	v_add_f32_e32 v3, v55, v3
	v_mfma_f32_16x16x32_bf16 v[8:11], v[16:19], v[4:7], 0
	v_add_f32_e32 v3, v67, v3
	v_add_f32_e32 v12, v142, v3
	v_sub_f32_e32 v3, v54, v0
	v_mfma_f32_16x16x32_bf16 v[16:19], v[24:27], v[4:7], 0
	v_add_u32_e32 v24, v115, v106
	v_add_u32_e32 v24, 0xe000, v24
	ds_read2_b64 v[24:27], v24 offset0:32 offset1:36
	v_mul_f32_e32 v3, 0x3fb8aa3b, v3
	v_sub_f32_e32 v1, v1, v0
	v_exp_f32_e32 v3, v3
	v_mul_f32_e32 v1, 0x3fb8aa3b, v1
	v_exp_f32_e32 v54, v1
	v_mul_f32_e32 v2, 0x3fb8aa3b, v2
	v_add_f32_e32 v12, v3, v12
	v_exp_f32_e32 v144, v2
	v_add_f32_e32 v1, v54, v12
	v_mfma_f32_16x16x32_bf16 v[12:15], v[20:23], v[4:7], 0
	v_cvt_pk_bf16_f32 v20, v48, v49
	v_cvt_pk_bf16_f32 v21, v50, v51
	v_cvt_pk_bf16_f32 v22, v44, v45
	v_cvt_pk_bf16_f32 v23, v46, v47
	v_mfma_f32_16x16x32_bf16 v[4:7], v[28:31], v[4:7], 0
	v_sub_f32_e32 v2, 0xf149f2ca, v0
	v_mul_f32_e32 v2, 0x3fb8aa3b, v2
	v_exp_f32_e32 v145, v2
	s_waitcnt lgkmcnt(0)
	v_mfma_f32_16x16x32_bf16 v[8:11], v[24:27], v[20:23], v[8:11]
	v_add_u32_e32 v24, v115, v108
	v_add_u32_e32 v24, 0xe000, v24
	ds_read2_b64 v[24:27], v24 offset0:32 offset1:36
	v_add_f32_e32 v1, v143, v1
	s_waitcnt lgkmcnt(0)
	v_mfma_f32_16x16x32_bf16 v[12:15], v[24:27], v[20:23], v[12:15]
	v_add_u32_e32 v24, v115, v109
	v_add_u32_e32 v24, 0xe000, v24
	ds_read2_b64 v[24:27], v24 offset0:32 offset1:36
	v_add_f32_e32 v1, v144, v1
	s_waitcnt lgkmcnt(0)
	v_mfma_f32_16x16x32_bf16 v[16:19], v[24:27], v[20:23], v[16:19]
	v_add_u32_e32 v24, v115, v110
	v_add_u32_e32 v24, 0xe000, v24
	ds_read2_b64 v[24:27], v24 offset0:32 offset1:36
	v_add_f32_e32 v1, v145, v1
	s_waitcnt lgkmcnt(0)
	v_mfma_f32_16x16x32_bf16 v[4:7], v[24:27], v[20:23], v[4:7]
	v_add_u32_e32 v24, v116, v106
	v_add_u32_e32 v24, 0xe000, v24
	ds_read2_b64 v[24:27], v24 offset0:32 offset1:36
	v_cvt_pk_bf16_f32 v20, v40, v41
	v_cvt_pk_bf16_f32 v21, v42, v43
	v_cvt_pk_bf16_f32 v22, v36, v37
	v_cvt_pk_bf16_f32 v23, v38, v39
	v_add_f32_e32 v1, v145, v1
	v_add_f32_e32 v1, v145, v1
	s_waitcnt lgkmcnt(0)
	v_mfma_f32_16x16x32_bf16 v[8:11], v[24:27], v[20:23], v[8:11]
	v_add_u32_e32 v24, v116, v108
	v_add_u32_e32 v24, 0xe000, v24
	ds_read2_b64 v[24:27], v24 offset0:32 offset1:36
	v_add_f32_e32 v1, v145, v1
	s_waitcnt lgkmcnt(0)
	v_mfma_f32_16x16x32_bf16 v[12:15], v[24:27], v[20:23], v[12:15]
	v_add_u32_e32 v24, v116, v109
	v_add_u32_e32 v24, 0xe000, v24
	ds_read2_b64 v[24:27], v24 offset0:32 offset1:36
	ds_bpermute_b32 v2, v119, v1
	s_waitcnt lgkmcnt(1)
	v_mfma_f32_16x16x32_bf16 v[16:19], v[24:27], v[20:23], v[16:19]
	v_add_u32_e32 v24, v116, v110
	v_add_u32_e32 v24, 0xe000, v24
	ds_read2_b64 v[24:27], v24 offset0:32 offset1:36
	s_waitcnt lgkmcnt(1)
	v_add_f32_e32 v1, v1, v2
	s_waitcnt lgkmcnt(0)
	v_mfma_f32_16x16x32_bf16 v[4:7], v[24:27], v[20:23], v[4:7]
	v_add_u32_e32 v24, v117, v106
	v_add_u32_e32 v24, 0xe000, v24
	ds_read2_b64 v[24:27], v24 offset0:32 offset1:36
	v_cvt_pk_bf16_f32 v20, v32, v33
	v_cvt_pk_bf16_f32 v21, v34, v35
	v_cvt_pk_bf16_f32 v22, v53, v55
	v_cvt_pk_bf16_f32 v23, v67, v142
	ds_bpermute_b32 v2, v120, v1
	s_waitcnt lgkmcnt(0)
	v_add_f32_e32 v1, v1, v2
	v_mfma_f32_16x16x32_bf16 v[8:11], v[24:27], v[20:23], v[8:11]
	v_add_u32_e32 v24, v117, v108
	v_add_u32_e32 v24, 0xe000, v24
	ds_read2_b64 v[24:27], v24 offset0:32 offset1:36
	v_rcp_f32_e32 v2, v1
	s_waitcnt lgkmcnt(0)
	v_mfma_f32_16x16x32_bf16 v[12:15], v[24:27], v[20:23], v[12:15]
	v_add_u32_e32 v24, v117, v109
	v_add_u32_e32 v24, 0xe000, v24
	ds_read2_b64 v[24:27], v24 offset0:32 offset1:36
	s_waitcnt lgkmcnt(0)
	v_mfma_f32_16x16x32_bf16 v[16:19], v[24:27], v[20:23], v[16:19]
	v_add_u32_e32 v24, v117, v110
	v_add_u32_e32 v24, 0xe000, v24
	ds_read2_b64 v[24:27], v24 offset0:32 offset1:36
	s_waitcnt lgkmcnt(0)
	v_mfma_f32_16x16x32_bf16 v[4:7], v[24:27], v[20:23], v[4:7]
	v_cvt_pk_bf16_f32 v20, v3, v54
	v_add_u32_e32 v3, v118, v106
	v_add_u32_e32 v3, 0xe000, v3
	ds_read2_b64 v[24:27], v3 offset0:32 offset1:36
	v_cvt_pk_bf16_f32 v22, v145, v145
	v_add_u32_e32 v3, v118, v108
	v_cvt_pk_bf16_f32 v21, v143, v144
	v_mov_b32_e32 v23, v22
	v_add_u32_e32 v3, 0xe000, v3
	s_waitcnt lgkmcnt(0)
	v_mfma_f32_16x16x32_bf16 v[8:11], v[24:27], v[20:23], v[8:11]
	ds_read2_b64 v[24:27], v3 offset0:32 offset1:36
	v_add_u32_e32 v3, v118, v109
	v_add_u32_e32 v3, 0xe000, v3
	s_waitcnt lgkmcnt(0)
	v_mfma_f32_16x16x32_bf16 v[12:15], v[24:27], v[20:23], v[12:15]
	ds_read2_b64 v[24:27], v3 offset0:32 offset1:36
	v_add_u32_e32 v3, v118, v110
	v_add_u32_e32 v3, 0xe000, v3
	s_waitcnt lgkmcnt(0)
	v_mfma_f32_16x16x32_bf16 v[16:19], v[24:27], v[20:23], v[16:19]
	ds_read2_b64 v[24:27], v3 offset0:32 offset1:36
	v_pk_mul_f32 v[8:9], v[8:9], v[2:3] op_sel_hi:[1,0]
	v_pk_mul_f32 v[10:11], v[10:11], v[2:3] op_sel_hi:[1,0]
	s_waitcnt lgkmcnt(0)
	v_mfma_f32_16x16x32_bf16 v[4:7], v[24:27], v[20:23], v[4:7]
	v_mad_i64_i32 v[20:21], s[20:21], v66, s82, v[64:65]
	v_cvt_pk_bf16_f32 v8, v8, v9
	v_cvt_pk_bf16_f32 v9, v10, v11
	global_store_dwordx2 v[20:21], v[8:9], off
	v_pk_mul_f32 v[8:9], v[12:13], v[2:3] op_sel_hi:[1,0]
	v_pk_mul_f32 v[10:11], v[14:15], v[2:3] op_sel_hi:[1,0]
	v_cvt_pk_bf16_f32 v8, v8, v9
	v_cvt_pk_bf16_f32 v9, v10, v11
	global_store_dwordx2 v[20:21], v[8:9], off offset:32
	v_pk_mul_f32 v[8:9], v[16:17], v[2:3] op_sel_hi:[1,0]
	v_pk_mul_f32 v[10:11], v[18:19], v[2:3] op_sel_hi:[1,0]
	v_pk_mul_f32 v[4:5], v[2:3], v[4:5] op_sel_hi:[0,1]
	v_pk_mul_f32 v[2:3], v[2:3], v[6:7] op_sel_hi:[0,1]
	v_cvt_pk_bf16_f32 v8, v8, v9
	v_cvt_pk_bf16_f32 v9, v10, v11
	v_cvt_pk_bf16_f32 v4, v4, v5
	v_cvt_pk_bf16_f32 v5, v2, v3
	global_store_dwordx2 v[20:21], v[8:9], off offset:64
	global_store_dwordx2 v[20:21], v[4:5], off offset:96
	s_and_saveexec_b64 s[20:21], vcc
	s_cbranch_execz .LBB0_522
	v_log_f32_e32 v1, v1
	v_ashrrev_i32_e32 v67, 31, v66
	v_lshlrev_b64 v[2:3], 5, v[66:67]
	v_lshl_add_u64 v[2:3], s[40:41], 0, v[2:3]
	v_fmac_f32_e32 v0, 0x3f317218, v1
	global_store_dword v[2:3], v0, off
	s_branch .LBB0_522
.LBB0_529:
	s_waitcnt vmcnt(0)
	s_mov_b64 s[78:79], s[66:67]
	v_readlane_b32 s88, v246, 51
	s_mov_b64 s[76:77], s[64:65]
	v_readlane_b32 s74, v246, 50
	v_readlane_b32 s89, v246, 52

	.amdhsa_kernel _Z6mk_fwd4Args
		.amdhsa_group_segment_fixed_size 0
		.amdhsa_private_segment_fixed_size 0
		.amdhsa_kernarg_size 400
		.amdhsa_user_sgpr_count 2
		.amdhsa_user_sgpr_dispatch_ptr 0
		.amdhsa_user_sgpr_queue_ptr 0
		.amdhsa_user_sgpr_kernarg_segment_ptr 1
		.amdhsa_user_sgpr_dispatch_id 0
		.amdhsa_user_sgpr_kernarg_preload_length 0
		.amdhsa_user_sgpr_kernarg_preload_offset 0
		.amdhsa_user_sgpr_private_segment_size 0
		.amdhsa_uses_dynamic_stack 0
		.amdhsa_enable_private_segment 0
		.amdhsa_system_sgpr_workgroup_id_x 1
		.amdhsa_system_sgpr_workgroup_id_y 0
		.amdhsa_system_sgpr_workgroup_id_z 0
		.amdhsa_system_sgpr_workgroup_info 0
		.amdhsa_system_vgpr_workitem_id 2
		.amdhsa_next_free_vgpr 256
		.amdhsa_next_free_sgpr 102
		.amdhsa_accum_offset 256
		.amdhsa_reserve_vcc 1
		.amdhsa_float_round_mode_32 0
		.amdhsa_float_round_mode_16_64 0
		.amdhsa_float_denorm_mode_32 3
		.amdhsa_float_denorm_mode_16_64 3
		.amdhsa_dx10_clamp 1
		.amdhsa_ieee_mode 1
		.amdhsa_fp16_overflow 0
		.amdhsa_tg_split 0
		.amdhsa_exception_fp_ieee_invalid_op 0
		.amdhsa_exception_fp_denorm_src 0
		.amdhsa_exception_fp_ieee_div_zero 0
		.amdhsa_exception_fp_ieee_overflow 0
		.amdhsa_exception_fp_ieee_underflow 0
		.amdhsa_exception_fp_ieee_inexact 0
		.amdhsa_exception_int_div_zero 0
	.end_amdhsa_kernel

amdhsa.kernels:
  - .agpr_count:     0
    .args:
      - .offset:         0
        .size:           144
        .value_kind:     by_value
      - .offset:         144
        .size:           4
        .value_kind:     hidden_block_count_x
      - .offset:         148
        .size:           4
        .value_kind:     hidden_block_count_y
      - .offset:         152
        .size:           4
        .value_kind:     hidden_block_count_z
      - .offset:         156
        .size:           2
        .value_kind:     hidden_group_size_x
      - .offset:         158
        .size:           2
        .value_kind:     hidden_group_size_y
      - .offset:         160
        .size:           2
        .value_kind:     hidden_group_size_z
      - .offset:         162
        .size:           2
        .value_kind:     hidden_remainder_x
      - .offset:         164
        .size:           2
        .value_kind:     hidden_remainder_y
      - .offset:         166
        .size:           2
        .value_kind:     hidden_remainder_z
      - .offset:         184
        .size:           8
        .value_kind:     hidden_global_offset_x
      - .offset:         192
        .size:           8
        .value_kind:     hidden_global_offset_y
      - .offset:         200
        .size:           8
        .value_kind:     hidden_global_offset_z
      - .offset:         208
        .size:           2
        .value_kind:     hidden_grid_dims
      - .offset:         232
        .size:           8
        .value_kind:     hidden_multigrid_sync_arg
      - .offset:         264
        .size:           4
        .value_kind:     hidden_dynamic_lds_size
    .group_segment_fixed_size: 0
    .kernarg_segment_align: 8
    .kernarg_segment_size: 400
    .language:       OpenCL C
    .language_version:
      - 2
      - 0
    .max_flat_workgroup_size: 512
    .name:           _Z6mk_fwd4Args
    .private_segment_fixed_size: 0
    .sgpr_count:     108
    .sgpr_spill_count: 58
    .symbol:         _Z6mk_fwd4Args.kd
    .uniform_work_group_size: 1
    .uses_dynamic_stack: false
    .vgpr_count:     256
    .vgpr_spill_count: 0
    .wavefront_size: 64
